# v50 + compiler's conservative s_waitcnt vmcnt(0) removed at K-loop heads: per tile in the unit-loop header of MLP2 x2 / WIN / HG_WO, every iteration of FN_WO's K-loop (+ its peeled copy), MLP1_0 prolo
# baseline (speedup 1.0000x reference)
.LBB0_565:
	v_readlane_b32 s62, v249, 27
	v_readlane_b32 s63, v249, 28
	s_add_u32 s72, s62, s68
	s_addc_u32 s73, s63, s69
	s_and_b64 s[62:63], s[70:71], exec
	s_cselect_b32 s31, s73, s77
	s_cselect_b32 s33, s72, s76
	s_add_u32 s74, s35, s66
	s_addc_u32 s75, s85, s67
	s_and_b64 s[62:63], s[70:71], exec
	s_cselect_b32 s34, s75, s79
	s_cselect_b32 s39, s74, s78
	s_add_i32 s45, s7, -2
	s_add_u32 s76, s76, 0x40080
	s_addc_u32 s77, s77, 0
	s_add_u32 s47, s78, 0x100
	s_addc_u32 s62, s79, 0
	s_mov_b32 s63, 0
	ds_read_b128 v[114:117], v190
	ds_read_b128 v[118:121], v190 offset:1024
	ds_read_b128 v[122:125], v190 offset:2048
	ds_read_b128 v[126:129], v190 offset:3072
	ds_read_b128 v[146:149], v191
	ds_read_b128 v[150:153], v191 offset:1024
	ds_read_b128 v[154:157], v191 offset:2048
	ds_read_b128 v[158:161], v191 offset:3072
	s_add_i32 s82, s63, 2
	s_add_u32 s78, s76, 0xfffc0080
	s_addc_u32 s79, s77, -1
	s_cmp_eq_u32 s45, s63
	s_cselect_b32 s81, s31, s79
	s_cselect_b32 s80, s33, s78
	s_cselect_b32 s79, s34, s62
	s_cselect_b32 s78, s39, s47
	v_lshl_add_u64 v[186:187], s[76:77], 0, v[180:181]
	s_add_i32 m0, s87, 0xc000
	ds_read_b128 v[162:165], v192
	ds_read_b128 v[166:169], v192 offset:1024
	ds_read_b128 v[194:197], v192 offset:2048
	ds_read_b128 v[198:201], v192 offset:3072
	ds_read_b128 v[206:209], v192 offset:4096
	ds_read_b128 v[210:213], v192 offset:5120
	ds_read_b128 v[214:217], v192 offset:6144
	ds_read_b128 v[218:221], v192 offset:7168
	global_load_lds_dwordx4 v[186:187], off
	v_lshl_add_u64 v[186:187], s[76:77], 0, v[182:183]
	s_add_i32 m0, s87, 0xe000
	s_nop 0
	global_load_lds_dwordx4 v[186:187], off
	s_waitcnt vmcnt(8)
	s_waitcnt lgkmcnt(0)
	s_barrier
	s_setprio 1
	s_waitcnt lgkmcnt(0)
	v_mfma_f32_16x16x32_bf16 v[142:145], v[114:117], v[162:165], 0
	v_mfma_f32_16x16x32_bf16 v[138:141], v[122:125], v[162:165], 0
	v_mfma_f32_16x16x32_bf16 v[110:113], v[114:117], v[194:197], 0
	v_mfma_f32_16x16x32_bf16 v[106:109], v[122:125], v[194:197], 0
	v_mfma_f32_16x16x32_bf16 v[98:101], v[114:117], v[206:209], 0
	v_mfma_f32_16x16x32_bf16 v[90:93], v[122:125], v[206:209], 0
	v_mfma_f32_16x16x32_bf16 v[82:85], v[114:117], v[214:217], 0
	v_mfma_f32_16x16x32_bf16 v[74:77], v[122:125], v[214:217], 0
	v_mfma_f32_16x16x32_bf16 v[142:145], v[118:121], v[166:169], v[142:145]
	v_mfma_f32_16x16x32_bf16 v[138:141], v[126:129], v[166:169], v[138:141]
	v_mfma_f32_16x16x32_bf16 v[110:113], v[118:121], v[198:201], v[110:113]
	v_mfma_f32_16x16x32_bf16 v[106:109], v[126:129], v[198:201], v[106:109]
	v_mfma_f32_16x16x32_bf16 v[98:101], v[118:121], v[210:213], v[98:101]
	v_mfma_f32_16x16x32_bf16 v[90:93], v[126:129], v[210:213], v[90:93]
	v_mfma_f32_16x16x32_bf16 v[82:85], v[118:121], v[218:221], v[82:85]
	v_mfma_f32_16x16x32_bf16 v[74:77], v[126:129], v[218:221], v[74:77]
	s_setprio 0
	s_setprio 1
	v_mfma_f32_16x16x32_bf16 v[134:137], v[146:149], v[162:165], 0
	v_mfma_f32_16x16x32_bf16 v[130:133], v[154:157], v[162:165], 0
	v_mfma_f32_16x16x32_bf16 v[102:105], v[146:149], v[194:197], 0
	v_mfma_f32_16x16x32_bf16 v[94:97], v[154:157], v[194:197], 0
	v_mfma_f32_16x16x32_bf16 v[86:89], v[146:149], v[206:209], 0
	v_mfma_f32_16x16x32_bf16 v[78:81], v[154:157], v[206:209], 0
	v_mfma_f32_16x16x32_bf16 v[70:73], v[146:149], v[214:217], 0
	v_mfma_f32_16x16x32_bf16 v[66:69], v[154:157], v[214:217], 0
	v_mfma_f32_16x16x32_bf16 v[134:137], v[150:153], v[166:169], v[134:137]
	v_mfma_f32_16x16x32_bf16 v[130:133], v[158:161], v[166:169], v[130:133]
	v_mfma_f32_16x16x32_bf16 v[102:105], v[150:153], v[198:201], v[102:105]
	v_mfma_f32_16x16x32_bf16 v[94:97], v[158:161], v[198:201], v[94:97]
	v_mfma_f32_16x16x32_bf16 v[86:89], v[150:153], v[210:213], v[86:89]
	v_mfma_f32_16x16x32_bf16 v[78:81], v[158:161], v[210:213], v[78:81]
	v_mfma_f32_16x16x32_bf16 v[70:73], v[150:153], v[218:221], v[70:73]
	v_mfma_f32_16x16x32_bf16 v[66:69], v[158:161], v[218:221], v[66:69]
	s_setprio 0
	s_barrier
	s_add_i32 s63, s24, s86
	v_lshl_add_u64 v[186:187], s[78:79], 0, v[172:173]
	s_mov_b32 m0, s63
	ds_read_b128 v[162:165], v192 offset:16384
	ds_read_b128 v[166:169], v192 offset:17408
	ds_read_b128 v[194:197], v192 offset:18432
	ds_read_b128 v[198:201], v192 offset:19456
	ds_read_b128 v[206:209], v192 offset:20480
	ds_read_b128 v[210:213], v192 offset:21504
	ds_read_b128 v[214:217], v192 offset:22528
	ds_read_b128 v[218:221], v192 offset:23552
	global_load_lds_dwordx4 v[186:187], off
	s_add_i32 m0, s63, 0x2000
	s_add_u32 vcc_lo, s78, 0x40000
	v_lshl_add_u64 v[202:203], s[78:79], 0, v[176:177]
	s_addc_u32 vcc_hi, s79, 0
	s_add_i32 s63, s25, s86
	global_load_lds_dwordx4 v[202:203], off
	v_lshl_add_u64 v[222:223], vcc, 0, v[172:173]
	s_mov_b32 m0, s63
	v_lshl_add_u64 v[224:225], s[80:81], 0, v[174:175]
	global_load_lds_dwordx4 v[222:223], off
	v_lshl_add_u64 v[222:223], vcc, 0, v[176:177]
	s_add_i32 m0, s63, 0x2000
	s_nop 0
	global_load_lds_dwordx4 v[222:223], off
	v_lshl_add_u64 v[222:223], s[80:81], 0, v[170:171]
	s_mov_b32 m0, s87
	s_nop 0
	global_load_lds_dwordx4 v[222:223], off
	s_mov_b32 m0, s88
	s_nop 0
	global_load_lds_dwordx4 v[224:225], off
	s_waitcnt vmcnt(8)
	s_waitcnt lgkmcnt(0)
	s_barrier
	s_setprio 1
	s_waitcnt lgkmcnt(0)
	v_mfma_f32_16x16x32_bf16 v[62:65], v[114:117], v[162:165], 0
	v_mfma_f32_16x16x32_bf16 v[58:61], v[122:125], v[162:165], 0
	v_mfma_f32_16x16x32_bf16 v[50:53], v[114:117], v[194:197], 0
	v_mfma_f32_16x16x32_bf16 v[42:45], v[122:125], v[194:197], 0
	v_mfma_f32_16x16x32_bf16 v[34:37], v[114:117], v[206:209], 0
	v_mfma_f32_16x16x32_bf16 v[26:29], v[122:125], v[206:209], 0
	v_mfma_f32_16x16x32_bf16 v[18:21], v[114:117], v[214:217], 0
	v_mfma_f32_16x16x32_bf16 v[10:13], v[122:125], v[214:217], 0
	v_mfma_f32_16x16x32_bf16 v[62:65], v[118:121], v[166:169], v[62:65]
	v_mfma_f32_16x16x32_bf16 v[58:61], v[126:129], v[166:169], v[58:61]
	v_mfma_f32_16x16x32_bf16 v[50:53], v[118:121], v[198:201], v[50:53]
	v_mfma_f32_16x16x32_bf16 v[42:45], v[126:129], v[198:201], v[42:45]
	v_mfma_f32_16x16x32_bf16 v[34:37], v[118:121], v[210:213], v[34:37]
	v_mfma_f32_16x16x32_bf16 v[26:29], v[126:129], v[210:213], v[26:29]
	v_mfma_f32_16x16x32_bf16 v[18:21], v[118:121], v[218:221], v[18:21]
	v_mfma_f32_16x16x32_bf16 v[10:13], v[126:129], v[218:221], v[10:13]
	s_setprio 0
	s_setprio 1
	v_mfma_f32_16x16x32_bf16 v[54:57], v[146:149], v[162:165], 0
	v_mfma_f32_16x16x32_bf16 v[46:49], v[154:157], v[162:165], 0
	v_mfma_f32_16x16x32_bf16 v[38:41], v[146:149], v[194:197], 0
	v_mfma_f32_16x16x32_bf16 v[30:33], v[154:157], v[194:197], 0
	v_mfma_f32_16x16x32_bf16 v[22:25], v[146:149], v[206:209], 0
	v_mfma_f32_16x16x32_bf16 v[14:17], v[154:157], v[206:209], 0
	v_mfma_f32_16x16x32_bf16 v[6:9], v[146:149], v[214:217], 0
	v_mfma_f32_16x16x32_bf16 v[2:5], v[154:157], v[214:217], 0
	v_mfma_f32_16x16x32_bf16 v[54:57], v[150:153], v[166:169], v[54:57]
	v_mfma_f32_16x16x32_bf16 v[46:49], v[158:161], v[166:169], v[46:49]
	v_mfma_f32_16x16x32_bf16 v[38:41], v[150:153], v[198:201], v[38:41]
	v_mfma_f32_16x16x32_bf16 v[30:33], v[158:161], v[198:201], v[30:33]
	v_mfma_f32_16x16x32_bf16 v[22:25], v[150:153], v[210:213], v[22:25]
	v_mfma_f32_16x16x32_bf16 v[14:17], v[158:161], v[210:213], v[14:17]
	v_mfma_f32_16x16x32_bf16 v[6:9], v[150:153], v[218:221], v[6:9]
	v_mfma_f32_16x16x32_bf16 v[2:5], v[158:161], v[218:221], v[2:5]
	s_setprio 0
	s_barrier
	s_add_i32 s63, 0, 0x18000
	s_add_i32 s83, 0, 0x1c000
	v_add_u32_e32 v126, s63, v189
	v_add_u32_e32 v158, s83, v189
	ds_read_b128 v[114:117], v126
	ds_read_b128 v[118:121], v126 offset:1024
	ds_read_b128 v[122:125], v126 offset:2048
	ds_read_b128 v[126:129], v126 offset:3072
	ds_read_b128 v[146:149], v158
	ds_read_b128 v[150:153], v158 offset:1024
	ds_read_b128 v[154:157], v158 offset:2048
	ds_read_b128 v[158:161], v158 offset:3072
	s_add_u32 s80, s80, 0x40000
	s_addc_u32 s81, s81, 0
	s_mov_b32 m0, s89
	v_lshl_add_u64 v[226:227], s[80:81], 0, v[170:171]
	ds_read_b128 v[162:165], v192 offset:32768
	ds_read_b128 v[166:169], v192 offset:33792
	ds_read_b128 v[194:197], v192 offset:34816
	ds_read_b128 v[198:201], v192 offset:35840
	ds_read_b128 v[206:209], v192 offset:36864
	ds_read_b128 v[210:213], v192 offset:37888
	ds_read_b128 v[214:217], v192 offset:38912
	ds_read_b128 v[218:221], v192 offset:39936
	global_load_lds_dwordx4 v[226:227], off
	v_lshl_add_u64 v[226:227], s[80:81], 0, v[174:175]
	s_mov_b32 m0, s90
	s_nop 0
	global_load_lds_dwordx4 v[226:227], off
	s_waitcnt vmcnt(8)
	s_waitcnt lgkmcnt(0)
	s_barrier
	s_setprio 1
	s_waitcnt lgkmcnt(0)
	v_mfma_f32_16x16x32_bf16 v[142:145], v[114:117], v[162:165], v[142:145]
	v_mfma_f32_16x16x32_bf16 v[138:141], v[122:125], v[162:165], v[138:141]
	v_mfma_f32_16x16x32_bf16 v[110:113], v[114:117], v[194:197], v[110:113]
	v_mfma_f32_16x16x32_bf16 v[106:109], v[122:125], v[194:197], v[106:109]
	v_mfma_f32_16x16x32_bf16 v[98:101], v[114:117], v[206:209], v[98:101]
	v_mfma_f32_16x16x32_bf16 v[90:93], v[122:125], v[206:209], v[90:93]
	v_mfma_f32_16x16x32_bf16 v[82:85], v[114:117], v[214:217], v[82:85]
	v_mfma_f32_16x16x32_bf16 v[74:77], v[122:125], v[214:217], v[74:77]
	v_mfma_f32_16x16x32_bf16 v[142:145], v[118:121], v[166:169], v[142:145]
	v_mfma_f32_16x16x32_bf16 v[138:141], v[126:129], v[166:169], v[138:141]
	v_mfma_f32_16x16x32_bf16 v[110:113], v[118:121], v[198:201], v[110:113]
	v_mfma_f32_16x16x32_bf16 v[106:109], v[126:129], v[198:201], v[106:109]
	v_mfma_f32_16x16x32_bf16 v[98:101], v[118:121], v[210:213], v[98:101]
	v_mfma_f32_16x16x32_bf16 v[90:93], v[126:129], v[210:213], v[90:93]
	v_mfma_f32_16x16x32_bf16 v[82:85], v[118:121], v[218:221], v[82:85]
	v_mfma_f32_16x16x32_bf16 v[74:77], v[126:129], v[218:221], v[74:77]
	s_setprio 0
	s_setprio 1
	v_mfma_f32_16x16x32_bf16 v[134:137], v[146:149], v[162:165], v[134:137]
	v_mfma_f32_16x16x32_bf16 v[130:133], v[154:157], v[162:165], v[130:133]
	v_mfma_f32_16x16x32_bf16 v[102:105], v[146:149], v[194:197], v[102:105]
	v_mfma_f32_16x16x32_bf16 v[94:97], v[154:157], v[194:197], v[94:97]
	v_mfma_f32_16x16x32_bf16 v[86:89], v[146:149], v[206:209], v[86:89]
	v_mfma_f32_16x16x32_bf16 v[78:81], v[154:157], v[206:209], v[78:81]
	v_mfma_f32_16x16x32_bf16 v[70:73], v[146:149], v[214:217], v[70:73]
	v_mfma_f32_16x16x32_bf16 v[66:69], v[154:157], v[214:217], v[66:69]
	v_mfma_f32_16x16x32_bf16 v[134:137], v[150:153], v[166:169], v[134:137]
	v_mfma_f32_16x16x32_bf16 v[130:133], v[158:161], v[166:169], v[130:133]
	v_mfma_f32_16x16x32_bf16 v[102:105], v[150:153], v[198:201], v[102:105]
	v_mfma_f32_16x16x32_bf16 v[94:97], v[158:161], v[198:201], v[94:97]
	v_mfma_f32_16x16x32_bf16 v[86:89], v[150:153], v[210:213], v[86:89]
	v_mfma_f32_16x16x32_bf16 v[78:81], v[158:161], v[210:213], v[78:81]
	v_mfma_f32_16x16x32_bf16 v[70:73], v[150:153], v[218:221], v[70:73]
	v_mfma_f32_16x16x32_bf16 v[66:69], v[158:161], v[218:221], v[66:69]
	s_setprio 0
	s_barrier
	s_add_i32 s63, s63, s86
	v_lshl_add_u64 v[186:187], v[186:187], 0, s[22:23]
	s_mov_b32 m0, s63
	ds_read_b128 v[162:165], v192 offset:49152
	ds_read_b128 v[166:169], v192 offset:50176
	ds_read_b128 v[194:197], v192 offset:51200
	ds_read_b128 v[198:201], v192 offset:52224
	ds_read_b128 v[206:209], v192 offset:53248
	ds_read_b128 v[210:213], v192 offset:54272
	ds_read_b128 v[214:217], v192 offset:55296
	ds_read_b128 v[218:221], v192 offset:56320
	global_load_lds_dwordx4 v[186:187], off
	s_add_i32 m0, s63, 0x2000
	s_add_u32 s78, s78, 0x40080
	v_lshl_add_u64 v[186:187], v[202:203], 0, s[22:23]
	s_addc_u32 s79, s79, 0
	s_add_i32 s63, s83, s86
	global_load_lds_dwordx4 v[186:187], off
	v_lshl_add_u64 v[186:187], s[78:79], 0, v[172:173]
	s_mov_b32 m0, s63
	s_nop 0
	global_load_lds_dwordx4 v[186:187], off
	v_lshl_add_u64 v[186:187], s[78:79], 0, v[176:177]
	s_add_i32 m0, s63, 0x2000
	s_nop 0
	global_load_lds_dwordx4 v[186:187], off
	v_lshl_add_u64 v[186:187], v[222:223], 0, s[22:23]
	s_mov_b32 m0, s95
	s_nop 0
	global_load_lds_dwordx4 v[186:187], off
	v_lshl_add_u64 v[186:187], v[224:225], 0, s[22:23]
	s_mov_b32 m0, s96
	s_nop 0
	global_load_lds_dwordx4 v[186:187], off
	s_waitcnt vmcnt(8)
	s_waitcnt lgkmcnt(0)
	s_barrier
	s_setprio 1
	s_waitcnt lgkmcnt(0)
	v_mfma_f32_16x16x32_bf16 v[62:65], v[114:117], v[162:165], v[62:65]
	v_mfma_f32_16x16x32_bf16 v[58:61], v[122:125], v[162:165], v[58:61]
	v_mfma_f32_16x16x32_bf16 v[50:53], v[114:117], v[194:197], v[50:53]
	v_mfma_f32_16x16x32_bf16 v[42:45], v[122:125], v[194:197], v[42:45]
	v_mfma_f32_16x16x32_bf16 v[34:37], v[114:117], v[206:209], v[34:37]
	v_mfma_f32_16x16x32_bf16 v[26:29], v[122:125], v[206:209], v[26:29]
	v_mfma_f32_16x16x32_bf16 v[18:21], v[114:117], v[214:217], v[18:21]
	v_mfma_f32_16x16x32_bf16 v[10:13], v[122:125], v[214:217], v[10:13]
	v_mfma_f32_16x16x32_bf16 v[62:65], v[118:121], v[166:169], v[62:65]
	v_mfma_f32_16x16x32_bf16 v[58:61], v[126:129], v[166:169], v[58:61]
	v_mfma_f32_16x16x32_bf16 v[50:53], v[118:121], v[198:201], v[50:53]
	v_mfma_f32_16x16x32_bf16 v[42:45], v[126:129], v[198:201], v[42:45]
	v_mfma_f32_16x16x32_bf16 v[34:37], v[118:121], v[210:213], v[34:37]
	v_mfma_f32_16x16x32_bf16 v[26:29], v[126:129], v[210:213], v[26:29]
	v_mfma_f32_16x16x32_bf16 v[18:21], v[118:121], v[218:221], v[18:21]
	v_mfma_f32_16x16x32_bf16 v[10:13], v[126:129], v[218:221], v[10:13]
	s_setprio 0
	s_setprio 1
	v_mfma_f32_16x16x32_bf16 v[54:57], v[146:149], v[162:165], v[54:57]
	v_mfma_f32_16x16x32_bf16 v[46:49], v[154:157], v[162:165], v[46:49]
	v_mfma_f32_16x16x32_bf16 v[38:41], v[146:149], v[194:197], v[38:41]
	v_mfma_f32_16x16x32_bf16 v[30:33], v[154:157], v[194:197], v[30:33]
	v_mfma_f32_16x16x32_bf16 v[22:25], v[146:149], v[206:209], v[22:25]
	v_mfma_f32_16x16x32_bf16 v[14:17], v[154:157], v[206:209], v[14:17]
	v_mfma_f32_16x16x32_bf16 v[6:9], v[146:149], v[214:217], v[6:9]
	v_mfma_f32_16x16x32_bf16 v[2:5], v[154:157], v[214:217], v[2:5]
	v_mfma_f32_16x16x32_bf16 v[54:57], v[150:153], v[166:169], v[54:57]
	v_mfma_f32_16x16x32_bf16 v[46:49], v[158:161], v[166:169], v[46:49]
	v_mfma_f32_16x16x32_bf16 v[38:41], v[150:153], v[198:201], v[38:41]
	v_mfma_f32_16x16x32_bf16 v[30:33], v[158:161], v[198:201], v[30:33]
	v_mfma_f32_16x16x32_bf16 v[22:25], v[150:153], v[210:213], v[22:25]
	v_mfma_f32_16x16x32_bf16 v[14:17], v[158:161], v[210:213], v[14:17]
	v_mfma_f32_16x16x32_bf16 v[6:9], v[150:153], v[218:221], v[6:9]
	v_mfma_f32_16x16x32_bf16 v[2:5], v[158:161], v[218:221], v[2:5]
	s_setprio 0
	s_barrier
	s_add_u32 s76, s76, 0x100
	s_addc_u32 s77, s77, 0
	s_add_u32 s47, s47, 0x100
	s_addc_u32 s62, s62, 0
	s_cmp_ge_i32 s82, s7
	s_mov_b32 s63, s82
.LBB0_566:
	ds_read_b128 v[114:117], v190
	ds_read_b128 v[118:121], v190 offset:1024
	ds_read_b128 v[122:125], v190 offset:2048
	ds_read_b128 v[126:129], v190 offset:3072
	ds_read_b128 v[146:149], v191
	ds_read_b128 v[150:153], v191 offset:1024
	ds_read_b128 v[154:157], v191 offset:2048
	ds_read_b128 v[158:161], v191 offset:3072
	s_add_i32 s82, s63, 2
	s_add_u32 s78, s76, 0xfffc0080
	s_addc_u32 s79, s77, -1
	s_cmp_eq_u32 s45, s63
	s_cselect_b32 s81, s31, s79
	s_cselect_b32 s80, s33, s78
	s_cselect_b32 s79, s34, s62
	s_cselect_b32 s78, s39, s47
	v_lshl_add_u64 v[186:187], s[76:77], 0, v[180:181]
	s_add_i32 m0, s87, 0xc000
	ds_read_b128 v[162:165], v192
	ds_read_b128 v[166:169], v192 offset:1024
	ds_read_b128 v[194:197], v192 offset:2048
	ds_read_b128 v[198:201], v192 offset:3072
	ds_read_b128 v[206:209], v192 offset:4096
	ds_read_b128 v[210:213], v192 offset:5120
	ds_read_b128 v[214:217], v192 offset:6144
	ds_read_b128 v[218:221], v192 offset:7168
	global_load_lds_dwordx4 v[186:187], off
	v_lshl_add_u64 v[186:187], s[76:77], 0, v[182:183]
	s_add_i32 m0, s87, 0xe000
	s_nop 0
	global_load_lds_dwordx4 v[186:187], off
	s_waitcnt vmcnt(8)
	s_waitcnt lgkmcnt(0)
	s_barrier
	s_setprio 1
	s_waitcnt lgkmcnt(0)
	v_mfma_f32_16x16x32_bf16 v[142:145], v[114:117], v[162:165], v[142:145]
	v_mfma_f32_16x16x32_bf16 v[138:141], v[122:125], v[162:165], v[138:141]
	v_mfma_f32_16x16x32_bf16 v[110:113], v[114:117], v[194:197], v[110:113]
	v_mfma_f32_16x16x32_bf16 v[106:109], v[122:125], v[194:197], v[106:109]
	v_mfma_f32_16x16x32_bf16 v[98:101], v[114:117], v[206:209], v[98:101]
	v_mfma_f32_16x16x32_bf16 v[90:93], v[122:125], v[206:209], v[90:93]
	v_mfma_f32_16x16x32_bf16 v[82:85], v[114:117], v[214:217], v[82:85]
	v_mfma_f32_16x16x32_bf16 v[74:77], v[122:125], v[214:217], v[74:77]
	v_mfma_f32_16x16x32_bf16 v[142:145], v[118:121], v[166:169], v[142:145]
	v_mfma_f32_16x16x32_bf16 v[138:141], v[126:129], v[166:169], v[138:141]
	v_mfma_f32_16x16x32_bf16 v[110:113], v[118:121], v[198:201], v[110:113]
	v_mfma_f32_16x16x32_bf16 v[106:109], v[126:129], v[198:201], v[106:109]
	v_mfma_f32_16x16x32_bf16 v[98:101], v[118:121], v[210:213], v[98:101]
	v_mfma_f32_16x16x32_bf16 v[90:93], v[126:129], v[210:213], v[90:93]
	v_mfma_f32_16x16x32_bf16 v[82:85], v[118:121], v[218:221], v[82:85]
	v_mfma_f32_16x16x32_bf16 v[74:77], v[126:129], v[218:221], v[74:77]
	s_setprio 0
	s_setprio 1
	v_mfma_f32_16x16x32_bf16 v[134:137], v[146:149], v[162:165], v[134:137]
	v_mfma_f32_16x16x32_bf16 v[130:133], v[154:157], v[162:165], v[130:133]
	v_mfma_f32_16x16x32_bf16 v[102:105], v[146:149], v[194:197], v[102:105]
	v_mfma_f32_16x16x32_bf16 v[94:97], v[154:157], v[194:197], v[94:97]
	v_mfma_f32_16x16x32_bf16 v[86:89], v[146:149], v[206:209], v[86:89]
	v_mfma_f32_16x16x32_bf16 v[78:81], v[154:157], v[206:209], v[78:81]
	v_mfma_f32_16x16x32_bf16 v[70:73], v[146:149], v[214:217], v[70:73]
	v_mfma_f32_16x16x32_bf16 v[66:69], v[154:157], v[214:217], v[66:69]
	v_mfma_f32_16x16x32_bf16 v[134:137], v[150:153], v[166:169], v[134:137]
	v_mfma_f32_16x16x32_bf16 v[130:133], v[158:161], v[166:169], v[130:133]
	v_mfma_f32_16x16x32_bf16 v[102:105], v[150:153], v[198:201], v[102:105]
	v_mfma_f32_16x16x32_bf16 v[94:97], v[158:161], v[198:201], v[94:97]
	v_mfma_f32_16x16x32_bf16 v[86:89], v[150:153], v[210:213], v[86:89]
	v_mfma_f32_16x16x32_bf16 v[78:81], v[158:161], v[210:213], v[78:81]
	v_mfma_f32_16x16x32_bf16 v[70:73], v[150:153], v[218:221], v[70:73]
	v_mfma_f32_16x16x32_bf16 v[66:69], v[158:161], v[218:221], v[66:69]
	s_setprio 0
	s_barrier
	s_add_i32 s63, s24, s86
	v_lshl_add_u64 v[186:187], s[78:79], 0, v[172:173]
	s_mov_b32 m0, s63
	ds_read_b128 v[162:165], v192 offset:16384
	ds_read_b128 v[166:169], v192 offset:17408
	ds_read_b128 v[194:197], v192 offset:18432
	ds_read_b128 v[198:201], v192 offset:19456
	ds_read_b128 v[206:209], v192 offset:20480
	ds_read_b128 v[210:213], v192 offset:21504
	ds_read_b128 v[214:217], v192 offset:22528
	ds_read_b128 v[218:221], v192 offset:23552
	global_load_lds_dwordx4 v[186:187], off
	s_add_i32 m0, s63, 0x2000
	s_add_u32 vcc_lo, s78, 0x40000
	v_lshl_add_u64 v[202:203], s[78:79], 0, v[176:177]
	s_addc_u32 vcc_hi, s79, 0
	s_add_i32 s63, s25, s86
	global_load_lds_dwordx4 v[202:203], off
	v_lshl_add_u64 v[222:223], vcc, 0, v[172:173]
	s_mov_b32 m0, s63
	v_lshl_add_u64 v[224:225], s[80:81], 0, v[174:175]
	global_load_lds_dwordx4 v[222:223], off
	v_lshl_add_u64 v[222:223], vcc, 0, v[176:177]
	s_add_i32 m0, s63, 0x2000
	s_nop 0
	global_load_lds_dwordx4 v[222:223], off
	v_lshl_add_u64 v[222:223], s[80:81], 0, v[170:171]
	s_mov_b32 m0, s87
	s_nop 0
	global_load_lds_dwordx4 v[222:223], off
	s_mov_b32 m0, s88
	s_nop 0
	global_load_lds_dwordx4 v[224:225], off
	s_waitcnt vmcnt(8)
	s_waitcnt lgkmcnt(0)
	s_barrier
	s_setprio 1
	s_waitcnt lgkmcnt(0)
	v_mfma_f32_16x16x32_bf16 v[62:65], v[114:117], v[162:165], v[62:65]
	v_mfma_f32_16x16x32_bf16 v[58:61], v[122:125], v[162:165], v[58:61]
	v_mfma_f32_16x16x32_bf16 v[50:53], v[114:117], v[194:197], v[50:53]
	v_mfma_f32_16x16x32_bf16 v[42:45], v[122:125], v[194:197], v[42:45]
	v_mfma_f32_16x16x32_bf16 v[34:37], v[114:117], v[206:209], v[34:37]
	v_mfma_f32_16x16x32_bf16 v[26:29], v[122:125], v[206:209], v[26:29]
	v_mfma_f32_16x16x32_bf16 v[18:21], v[114:117], v[214:217], v[18:21]
	v_mfma_f32_16x16x32_bf16 v[10:13], v[122:125], v[214:217], v[10:13]
	v_mfma_f32_16x16x32_bf16 v[62:65], v[118:121], v[166:169], v[62:65]
	v_mfma_f32_16x16x32_bf16 v[58:61], v[126:129], v[166:169], v[58:61]
	v_mfma_f32_16x16x32_bf16 v[50:53], v[118:121], v[198:201], v[50:53]
	v_mfma_f32_16x16x32_bf16 v[42:45], v[126:129], v[198:201], v[42:45]
	v_mfma_f32_16x16x32_bf16 v[34:37], v[118:121], v[210:213], v[34:37]
	v_mfma_f32_16x16x32_bf16 v[26:29], v[126:129], v[210:213], v[26:29]
	v_mfma_f32_16x16x32_bf16 v[18:21], v[118:121], v[218:221], v[18:21]
	v_mfma_f32_16x16x32_bf16 v[10:13], v[126:129], v[218:221], v[10:13]
	s_setprio 0
	s_setprio 1
	v_mfma_f32_16x16x32_bf16 v[54:57], v[146:149], v[162:165], v[54:57]
	v_mfma_f32_16x16x32_bf16 v[46:49], v[154:157], v[162:165], v[46:49]
	v_mfma_f32_16x16x32_bf16 v[38:41], v[146:149], v[194:197], v[38:41]
	v_mfma_f32_16x16x32_bf16 v[30:33], v[154:157], v[194:197], v[30:33]
	v_mfma_f32_16x16x32_bf16 v[22:25], v[146:149], v[206:209], v[22:25]
	v_mfma_f32_16x16x32_bf16 v[14:17], v[154:157], v[206:209], v[14:17]
	v_mfma_f32_16x16x32_bf16 v[6:9], v[146:149], v[214:217], v[6:9]
	v_mfma_f32_16x16x32_bf16 v[2:5], v[154:157], v[214:217], v[2:5]
	v_mfma_f32_16x16x32_bf16 v[54:57], v[150:153], v[166:169], v[54:57]
	v_mfma_f32_16x16x32_bf16 v[46:49], v[158:161], v[166:169], v[46:49]
	v_mfma_f32_16x16x32_bf16 v[38:41], v[150:153], v[198:201], v[38:41]
	v_mfma_f32_16x16x32_bf16 v[30:33], v[158:161], v[198:201], v[30:33]
	v_mfma_f32_16x16x32_bf16 v[22:25], v[150:153], v[210:213], v[22:25]
	v_mfma_f32_16x16x32_bf16 v[14:17], v[158:161], v[210:213], v[14:17]
	v_mfma_f32_16x16x32_bf16 v[6:9], v[150:153], v[218:221], v[6:9]
	v_mfma_f32_16x16x32_bf16 v[2:5], v[158:161], v[218:221], v[2:5]
	s_setprio 0
	s_barrier
	s_add_i32 s63, 0, 0x18000
	s_add_i32 s83, 0, 0x1c000
	v_add_u32_e32 v126, s63, v189
	v_add_u32_e32 v158, s83, v189
	ds_read_b128 v[114:117], v126
	ds_read_b128 v[118:121], v126 offset:1024
	ds_read_b128 v[122:125], v126 offset:2048
	ds_read_b128 v[126:129], v126 offset:3072
	ds_read_b128 v[146:149], v158
	ds_read_b128 v[150:153], v158 offset:1024
	ds_read_b128 v[154:157], v158 offset:2048
	ds_read_b128 v[158:161], v158 offset:3072
	s_add_u32 s80, s80, 0x40000
	s_addc_u32 s81, s81, 0
	s_mov_b32 m0, s89
	v_lshl_add_u64 v[226:227], s[80:81], 0, v[170:171]
	ds_read_b128 v[162:165], v192 offset:32768
	ds_read_b128 v[166:169], v192 offset:33792
	ds_read_b128 v[194:197], v192 offset:34816
	ds_read_b128 v[198:201], v192 offset:35840
	ds_read_b128 v[206:209], v192 offset:36864
	ds_read_b128 v[210:213], v192 offset:37888
	ds_read_b128 v[214:217], v192 offset:38912
	ds_read_b128 v[218:221], v192 offset:39936
	global_load_lds_dwordx4 v[226:227], off
	v_lshl_add_u64 v[226:227], s[80:81], 0, v[174:175]
	s_mov_b32 m0, s90
	s_nop 0
	global_load_lds_dwordx4 v[226:227], off
	s_waitcnt vmcnt(8)
	s_waitcnt lgkmcnt(0)
	s_barrier
	s_setprio 1
	s_waitcnt lgkmcnt(0)
	v_mfma_f32_16x16x32_bf16 v[142:145], v[114:117], v[162:165], v[142:145]
	v_mfma_f32_16x16x32_bf16 v[138:141], v[122:125], v[162:165], v[138:141]
	v_mfma_f32_16x16x32_bf16 v[110:113], v[114:117], v[194:197], v[110:113]
	v_mfma_f32_16x16x32_bf16 v[106:109], v[122:125], v[194:197], v[106:109]
	v_mfma_f32_16x16x32_bf16 v[98:101], v[114:117], v[206:209], v[98:101]
	v_mfma_f32_16x16x32_bf16 v[90:93], v[122:125], v[206:209], v[90:93]
	v_mfma_f32_16x16x32_bf16 v[82:85], v[114:117], v[214:217], v[82:85]
	v_mfma_f32_16x16x32_bf16 v[74:77], v[122:125], v[214:217], v[74:77]
	v_mfma_f32_16x16x32_bf16 v[142:145], v[118:121], v[166:169], v[142:145]
	v_mfma_f32_16x16x32_bf16 v[138:141], v[126:129], v[166:169], v[138:141]
	v_mfma_f32_16x16x32_bf16 v[110:113], v[118:121], v[198:201], v[110:113]
	v_mfma_f32_16x16x32_bf16 v[106:109], v[126:129], v[198:201], v[106:109]
	v_mfma_f32_16x16x32_bf16 v[98:101], v[118:121], v[210:213], v[98:101]
	v_mfma_f32_16x16x32_bf16 v[90:93], v[126:129], v[210:213], v[90:93]
	v_mfma_f32_16x16x32_bf16 v[82:85], v[118:121], v[218:221], v[82:85]
	v_mfma_f32_16x16x32_bf16 v[74:77], v[126:129], v[218:221], v[74:77]
	s_setprio 0
	s_setprio 1
	v_mfma_f32_16x16x32_bf16 v[134:137], v[146:149], v[162:165], v[134:137]
	v_mfma_f32_16x16x32_bf16 v[130:133], v[154:157], v[162:165], v[130:133]
	v_mfma_f32_16x16x32_bf16 v[102:105], v[146:149], v[194:197], v[102:105]
	v_mfma_f32_16x16x32_bf16 v[94:97], v[154:157], v[194:197], v[94:97]
	v_mfma_f32_16x16x32_bf16 v[86:89], v[146:149], v[206:209], v[86:89]
	v_mfma_f32_16x16x32_bf16 v[78:81], v[154:157], v[206:209], v[78:81]
	v_mfma_f32_16x16x32_bf16 v[70:73], v[146:149], v[214:217], v[70:73]
	v_mfma_f32_16x16x32_bf16 v[66:69], v[154:157], v[214:217], v[66:69]
	v_mfma_f32_16x16x32_bf16 v[134:137], v[150:153], v[166:169], v[134:137]
	v_mfma_f32_16x16x32_bf16 v[130:133], v[158:161], v[166:169], v[130:133]
	v_mfma_f32_16x16x32_bf16 v[102:105], v[150:153], v[198:201], v[102:105]
	v_mfma_f32_16x16x32_bf16 v[94:97], v[158:161], v[198:201], v[94:97]
	v_mfma_f32_16x16x32_bf16 v[86:89], v[150:153], v[210:213], v[86:89]
	v_mfma_f32_16x16x32_bf16 v[78:81], v[158:161], v[210:213], v[78:81]
	v_mfma_f32_16x16x32_bf16 v[70:73], v[150:153], v[218:221], v[70:73]
	v_mfma_f32_16x16x32_bf16 v[66:69], v[158:161], v[218:221], v[66:69]
	s_setprio 0
	s_barrier
	s_add_i32 s63, s63, s86
	v_lshl_add_u64 v[186:187], v[186:187], 0, s[22:23]
	s_mov_b32 m0, s63
	ds_read_b128 v[162:165], v192 offset:49152
	ds_read_b128 v[166:169], v192 offset:50176
	ds_read_b128 v[194:197], v192 offset:51200
	ds_read_b128 v[198:201], v192 offset:52224
	ds_read_b128 v[206:209], v192 offset:53248
	ds_read_b128 v[210:213], v192 offset:54272
	ds_read_b128 v[214:217], v192 offset:55296
	ds_read_b128 v[218:221], v192 offset:56320
	global_load_lds_dwordx4 v[186:187], off
	s_add_i32 m0, s63, 0x2000
	s_add_u32 s78, s78, 0x40080
	v_lshl_add_u64 v[186:187], v[202:203], 0, s[22:23]
	s_addc_u32 s79, s79, 0
	s_add_i32 s63, s83, s86
	global_load_lds_dwordx4 v[186:187], off
	v_lshl_add_u64 v[186:187], s[78:79], 0, v[172:173]
	s_mov_b32 m0, s63
	s_nop 0
	global_load_lds_dwordx4 v[186:187], off
	v_lshl_add_u64 v[186:187], s[78:79], 0, v[176:177]
	s_add_i32 m0, s63, 0x2000
	s_nop 0
	global_load_lds_dwordx4 v[186:187], off
	v_lshl_add_u64 v[186:187], v[222:223], 0, s[22:23]
	s_mov_b32 m0, s95
	s_nop 0
	global_load_lds_dwordx4 v[186:187], off
	v_lshl_add_u64 v[186:187], v[224:225], 0, s[22:23]
	s_mov_b32 m0, s96
	s_nop 0
	global_load_lds_dwordx4 v[186:187], off
	s_waitcnt vmcnt(8)
	s_waitcnt lgkmcnt(0)
	s_barrier
	s_setprio 1
	s_waitcnt lgkmcnt(0)
	v_mfma_f32_16x16x32_bf16 v[62:65], v[114:117], v[162:165], v[62:65]
	v_mfma_f32_16x16x32_bf16 v[58:61], v[122:125], v[162:165], v[58:61]
	v_mfma_f32_16x16x32_bf16 v[50:53], v[114:117], v[194:197], v[50:53]
	v_mfma_f32_16x16x32_bf16 v[42:45], v[122:125], v[194:197], v[42:45]
	v_mfma_f32_16x16x32_bf16 v[34:37], v[114:117], v[206:209], v[34:37]
	v_mfma_f32_16x16x32_bf16 v[26:29], v[122:125], v[206:209], v[26:29]
	v_mfma_f32_16x16x32_bf16 v[18:21], v[114:117], v[214:217], v[18:21]
	v_mfma_f32_16x16x32_bf16 v[10:13], v[122:125], v[214:217], v[10:13]
	v_mfma_f32_16x16x32_bf16 v[62:65], v[118:121], v[166:169], v[62:65]
	v_mfma_f32_16x16x32_bf16 v[58:61], v[126:129], v[166:169], v[58:61]
	v_mfma_f32_16x16x32_bf16 v[50:53], v[118:121], v[198:201], v[50:53]
	v_mfma_f32_16x16x32_bf16 v[42:45], v[126:129], v[198:201], v[42:45]
	v_mfma_f32_16x16x32_bf16 v[34:37], v[118:121], v[210:213], v[34:37]
	v_mfma_f32_16x16x32_bf16 v[26:29], v[126:129], v[210:213], v[26:29]
	v_mfma_f32_16x16x32_bf16 v[18:21], v[118:121], v[218:221], v[18:21]
	v_mfma_f32_16x16x32_bf16 v[10:13], v[126:129], v[218:221], v[10:13]
	s_setprio 0
	s_setprio 1
	v_mfma_f32_16x16x32_bf16 v[54:57], v[146:149], v[162:165], v[54:57]
	v_mfma_f32_16x16x32_bf16 v[46:49], v[154:157], v[162:165], v[46:49]
	v_mfma_f32_16x16x32_bf16 v[38:41], v[146:149], v[194:197], v[38:41]
	v_mfma_f32_16x16x32_bf16 v[30:33], v[154:157], v[194:197], v[30:33]
	v_mfma_f32_16x16x32_bf16 v[22:25], v[146:149], v[206:209], v[22:25]
	v_mfma_f32_16x16x32_bf16 v[14:17], v[154:157], v[206:209], v[14:17]
	v_mfma_f32_16x16x32_bf16 v[6:9], v[146:149], v[214:217], v[6:9]
	v_mfma_f32_16x16x32_bf16 v[2:5], v[154:157], v[214:217], v[2:5]
	v_mfma_f32_16x16x32_bf16 v[54:57], v[150:153], v[166:169], v[54:57]
	v_mfma_f32_16x16x32_bf16 v[46:49], v[158:161], v[166:169], v[46:49]
	v_mfma_f32_16x16x32_bf16 v[38:41], v[150:153], v[198:201], v[38:41]
	v_mfma_f32_16x16x32_bf16 v[30:33], v[158:161], v[198:201], v[30:33]
	v_mfma_f32_16x16x32_bf16 v[22:25], v[150:153], v[210:213], v[22:25]
	v_mfma_f32_16x16x32_bf16 v[14:17], v[158:161], v[210:213], v[14:17]
	v_mfma_f32_16x16x32_bf16 v[6:9], v[150:153], v[218:221], v[6:9]
	v_mfma_f32_16x16x32_bf16 v[2:5], v[158:161], v[218:221], v[2:5]
	s_setprio 0
	s_barrier
	s_add_u32 s76, s76, 0x100
	s_addc_u32 s77, s77, 0
	s_add_u32 s47, s47, 0x100
	s_addc_u32 s62, s62, 0
	s_cmp_ge_i32 s82, s7
	s_mov_b32 s63, s82
	s_cbranch_scc0 .LBB0_566
	s_and_b64 vcc, exec, s[26:27]
	s_cbranch_vccz .LBB0_569
	s_barrier

.LBB0_739:
	s_lshl_b32 s10, s10, 5
	s_lshl_b32 s30, s11, 6
	s_lshl_b32 s14, s11, 13
	s_and_b32 s31, s10, 0x60
	s_mov_b64 s[10:11], 0x80
	s_add_i32 m0, s19, 0x18000
	v_lshl_add_u64 v[8:9], v[8:9], 0, s[10:11]
	s_lshl_b32 s15, s31, 7
	s_waitcnt vmcnt(2)
	s_barrier
	global_load_lds_dwordx4 v[8:9], off
	v_lshl_add_u64 v[6:7], v[6:7], 0, s[10:11]
	s_add_i32 m0, s19, 0x1a000
	s_add_i32 s33, s19, 0x8000
	s_add_i32 s35, s19, 0xa000
	global_load_lds_dwordx4 v[6:7], off
	v_lshl_add_u64 v[2:3], v[2:3], 0, s[10:11]
	s_mov_b32 m0, s33
	s_add_u32 s12, s44, 0x40080
	global_load_lds_dwordx4 v[2:3], off
	v_lshl_add_u64 v[2:3], v[4:5], 0, s[10:11]
	s_mov_b32 m0, s35
	s_addc_u32 s13, s45, 0
	global_load_lds_dwordx4 v[2:3], off
	s_add_i32 m0, s19, 0x1c000
	v_lshl_add_u64 v[2:3], s[12:13], 0, v[134:135]
	global_load_lds_dwordx4 v[2:3], off
	v_lshl_add_u64 v[2:3], s[12:13], 0, v[130:131]
	s_add_i32 m0, s19, 0x1e000
	v_bfe_u32 v148, v0, 4, 2
	global_load_lds_dwordx4 v[2:3], off
	s_sext_i32_i8 s64, s4
	v_and_b32_e32 v1, 15, v0
	v_lshlrev_b32_e32 v2, 4, v148
	v_lshlrev_b32_e32 v4, 2, v0
	v_lshlrev_b32_e32 v5, 6, v0
	s_movk_i32 s4, 0x3c0
	v_lshl_or_b32 v3, v1, 6, v2
	v_and_b32_e32 v4, 32, v4
	v_and_or_b32 v2, v5, s4, v2
	v_bitop3_b32 v149, s15, v2, v4 bitop3:0xf6
	v_lshlrev_b32_e32 v2, 8, v0
	v_bitop3_b32 v3, v3, s14, v4 bitop3:0xde
	s_waitcnt vmcnt(6)
	s_cmpk_lt_u32 s5, 0x100
	v_and_b32_e32 v2, 0x18000, v2
	v_lshlrev_b32_e32 v4, 11, v12
	s_cselect_b64 s[12:13], -1, 0
	v_readlane_b32 s4, v249, 2
	v_or3_b32 v2, v10, v2, v4
	s_add_i32 s49, 0, 0x10000
	s_add_i32 s62, 0, 0x14000
	s_ashr_i32 s48, s4, 31
	v_add_u32_e32 v138, v2, v11
	v_mov_b32_e32 v139, v135
	v_add3_u32 v140, v13, v10, v11
	v_mov_b32_e32 v141, v135
	v_mov_b64_e32 v[142:143], 0x500
	v_mov_b64_e32 v[144:145], 0x4ff
	v_add_u32_e32 v150, s49, v149
	v_add_u32_e32 v151, s62, v149
	v_add_u32_e32 v152, 0, v3
	s_barrier
	v_readlane_b32 s5, v249, 3
	s_branch .LBB0_742

.LBB0_833:
	s_add_u32 s72, s0, s68
	s_addc_u32 s73, s1, s69
	s_and_b64 s[62:63], s[70:71], exec
	s_cselect_b32 s15, s73, s77
	s_cselect_b32 s33, s72, s76
	s_add_u32 s74, s35, s66
	s_addc_u32 s75, s85, s67
	s_and_b64 s[62:63], s[70:71], exec
	s_cselect_b32 s34, s75, s79
	s_cselect_b32 s39, s74, s78
	s_add_i32 s45, s7, -2
	s_add_u32 s76, s76, 0x100080
	s_addc_u32 s77, s77, 0
	s_add_u32 s47, s78, 0x100
	s_addc_u32 s62, s79, 0
	s_mov_b32 s63, 0
	ds_read_b128 v[114:117], v190
	ds_read_b128 v[118:121], v190 offset:1024
	ds_read_b128 v[122:125], v190 offset:2048
	ds_read_b128 v[126:129], v190 offset:3072
	ds_read_b128 v[146:149], v191
	ds_read_b128 v[150:153], v191 offset:1024
	ds_read_b128 v[154:157], v191 offset:2048
	ds_read_b128 v[158:161], v191 offset:3072
	s_add_i32 s82, s63, 2
	s_add_u32 s78, s76, 0xfff00080
	s_addc_u32 s79, s77, -1
	s_cmp_eq_u32 s45, s63
	s_cselect_b32 s81, s15, s79
	s_cselect_b32 s80, s33, s78
	s_cselect_b32 s79, s34, s62
	s_cselect_b32 s78, s39, s47
	v_lshl_add_u64 v[186:187], s[76:77], 0, v[180:181]
	s_add_i32 m0, s87, 0xc000
	ds_read_b128 v[162:165], v192
	ds_read_b128 v[166:169], v192 offset:1024
	ds_read_b128 v[194:197], v192 offset:2048
	ds_read_b128 v[198:201], v192 offset:3072
	ds_read_b128 v[206:209], v192 offset:4096
	ds_read_b128 v[210:213], v192 offset:5120
	ds_read_b128 v[214:217], v192 offset:6144
	ds_read_b128 v[218:221], v192 offset:7168
	global_load_lds_dwordx4 v[186:187], off
	v_lshl_add_u64 v[186:187], s[76:77], 0, v[182:183]
	s_add_i32 m0, s87, 0xe000
	s_nop 0
	global_load_lds_dwordx4 v[186:187], off
	s_waitcnt vmcnt(8)
	s_waitcnt lgkmcnt(0)
	s_barrier
	s_setprio 1
	s_waitcnt lgkmcnt(0)
	v_mfma_f32_16x16x32_bf16 v[142:145], v[114:117], v[162:165], 0
	v_mfma_f32_16x16x32_bf16 v[138:141], v[122:125], v[162:165], 0
	v_mfma_f32_16x16x32_bf16 v[110:113], v[114:117], v[194:197], 0
	v_mfma_f32_16x16x32_bf16 v[106:109], v[122:125], v[194:197], 0
	v_mfma_f32_16x16x32_bf16 v[98:101], v[114:117], v[206:209], 0
	v_mfma_f32_16x16x32_bf16 v[90:93], v[122:125], v[206:209], 0
	v_mfma_f32_16x16x32_bf16 v[82:85], v[114:117], v[214:217], 0
	v_mfma_f32_16x16x32_bf16 v[74:77], v[122:125], v[214:217], 0
	v_mfma_f32_16x16x32_bf16 v[142:145], v[118:121], v[166:169], v[142:145]
	v_mfma_f32_16x16x32_bf16 v[138:141], v[126:129], v[166:169], v[138:141]
	v_mfma_f32_16x16x32_bf16 v[110:113], v[118:121], v[198:201], v[110:113]
	v_mfma_f32_16x16x32_bf16 v[106:109], v[126:129], v[198:201], v[106:109]
	v_mfma_f32_16x16x32_bf16 v[98:101], v[118:121], v[210:213], v[98:101]
	v_mfma_f32_16x16x32_bf16 v[90:93], v[126:129], v[210:213], v[90:93]
	v_mfma_f32_16x16x32_bf16 v[82:85], v[118:121], v[218:221], v[82:85]
	v_mfma_f32_16x16x32_bf16 v[74:77], v[126:129], v[218:221], v[74:77]
	s_setprio 0
	s_setprio 1
	v_mfma_f32_16x16x32_bf16 v[134:137], v[146:149], v[162:165], 0
	v_mfma_f32_16x16x32_bf16 v[130:133], v[154:157], v[162:165], 0
	v_mfma_f32_16x16x32_bf16 v[102:105], v[146:149], v[194:197], 0
	v_mfma_f32_16x16x32_bf16 v[94:97], v[154:157], v[194:197], 0
	v_mfma_f32_16x16x32_bf16 v[86:89], v[146:149], v[206:209], 0
	v_mfma_f32_16x16x32_bf16 v[78:81], v[154:157], v[206:209], 0
	v_mfma_f32_16x16x32_bf16 v[70:73], v[146:149], v[214:217], 0
	v_mfma_f32_16x16x32_bf16 v[66:69], v[154:157], v[214:217], 0
	v_mfma_f32_16x16x32_bf16 v[134:137], v[150:153], v[166:169], v[134:137]
	v_mfma_f32_16x16x32_bf16 v[130:133], v[158:161], v[166:169], v[130:133]
	v_mfma_f32_16x16x32_bf16 v[102:105], v[150:153], v[198:201], v[102:105]
	v_mfma_f32_16x16x32_bf16 v[94:97], v[158:161], v[198:201], v[94:97]
	v_mfma_f32_16x16x32_bf16 v[86:89], v[150:153], v[210:213], v[86:89]
	v_mfma_f32_16x16x32_bf16 v[78:81], v[158:161], v[210:213], v[78:81]
	v_mfma_f32_16x16x32_bf16 v[70:73], v[150:153], v[218:221], v[70:73]
	v_mfma_f32_16x16x32_bf16 v[66:69], v[158:161], v[218:221], v[66:69]
	s_setprio 0
	s_barrier
	s_add_i32 s63, s24, s86
	v_lshl_add_u64 v[186:187], s[78:79], 0, v[172:173]
	s_mov_b32 m0, s63
	ds_read_b128 v[162:165], v192 offset:16384
	ds_read_b128 v[166:169], v192 offset:17408
	ds_read_b128 v[194:197], v192 offset:18432
	ds_read_b128 v[198:201], v192 offset:19456
	ds_read_b128 v[206:209], v192 offset:20480
	ds_read_b128 v[210:213], v192 offset:21504
	ds_read_b128 v[214:217], v192 offset:22528
	ds_read_b128 v[218:221], v192 offset:23552
	global_load_lds_dwordx4 v[186:187], off
	s_add_i32 m0, s63, 0x2000
	s_add_u32 vcc_lo, s78, 0x100000
	v_lshl_add_u64 v[202:203], s[78:79], 0, v[176:177]
	s_addc_u32 vcc_hi, s79, 0
	s_add_i32 s63, s25, s86
	global_load_lds_dwordx4 v[202:203], off
	v_lshl_add_u64 v[222:223], vcc, 0, v[172:173]
	s_mov_b32 m0, s63
	v_lshl_add_u64 v[224:225], s[80:81], 0, v[174:175]
	global_load_lds_dwordx4 v[222:223], off
	v_lshl_add_u64 v[222:223], vcc, 0, v[176:177]
	s_add_i32 m0, s63, 0x2000
	s_nop 0
	global_load_lds_dwordx4 v[222:223], off
	v_lshl_add_u64 v[222:223], s[80:81], 0, v[170:171]
	s_mov_b32 m0, s87
	s_nop 0
	global_load_lds_dwordx4 v[222:223], off
	s_mov_b32 m0, s88
	s_nop 0
	global_load_lds_dwordx4 v[224:225], off
	s_waitcnt vmcnt(8)
	s_waitcnt lgkmcnt(0)
	s_barrier
	s_setprio 1
	s_waitcnt lgkmcnt(0)
	v_mfma_f32_16x16x32_bf16 v[62:65], v[114:117], v[162:165], 0
	v_mfma_f32_16x16x32_bf16 v[58:61], v[122:125], v[162:165], 0
	v_mfma_f32_16x16x32_bf16 v[50:53], v[114:117], v[194:197], 0
	v_mfma_f32_16x16x32_bf16 v[42:45], v[122:125], v[194:197], 0
	v_mfma_f32_16x16x32_bf16 v[34:37], v[114:117], v[206:209], 0
	v_mfma_f32_16x16x32_bf16 v[26:29], v[122:125], v[206:209], 0
	v_mfma_f32_16x16x32_bf16 v[18:21], v[114:117], v[214:217], 0
	v_mfma_f32_16x16x32_bf16 v[10:13], v[122:125], v[214:217], 0
	v_mfma_f32_16x16x32_bf16 v[62:65], v[118:121], v[166:169], v[62:65]
	v_mfma_f32_16x16x32_bf16 v[58:61], v[126:129], v[166:169], v[58:61]
	v_mfma_f32_16x16x32_bf16 v[50:53], v[118:121], v[198:201], v[50:53]
	v_mfma_f32_16x16x32_bf16 v[42:45], v[126:129], v[198:201], v[42:45]
	v_mfma_f32_16x16x32_bf16 v[34:37], v[118:121], v[210:213], v[34:37]
	v_mfma_f32_16x16x32_bf16 v[26:29], v[126:129], v[210:213], v[26:29]
	v_mfma_f32_16x16x32_bf16 v[18:21], v[118:121], v[218:221], v[18:21]
	v_mfma_f32_16x16x32_bf16 v[10:13], v[126:129], v[218:221], v[10:13]
	s_setprio 0
	s_setprio 1
	v_mfma_f32_16x16x32_bf16 v[54:57], v[146:149], v[162:165], 0
	v_mfma_f32_16x16x32_bf16 v[46:49], v[154:157], v[162:165], 0
	v_mfma_f32_16x16x32_bf16 v[38:41], v[146:149], v[194:197], 0
	v_mfma_f32_16x16x32_bf16 v[30:33], v[154:157], v[194:197], 0
	v_mfma_f32_16x16x32_bf16 v[22:25], v[146:149], v[206:209], 0
	v_mfma_f32_16x16x32_bf16 v[14:17], v[154:157], v[206:209], 0
	v_mfma_f32_16x16x32_bf16 v[6:9], v[146:149], v[214:217], 0
	v_mfma_f32_16x16x32_bf16 v[2:5], v[154:157], v[214:217], 0
	v_mfma_f32_16x16x32_bf16 v[54:57], v[150:153], v[166:169], v[54:57]
	v_mfma_f32_16x16x32_bf16 v[46:49], v[158:161], v[166:169], v[46:49]
	v_mfma_f32_16x16x32_bf16 v[38:41], v[150:153], v[198:201], v[38:41]
	v_mfma_f32_16x16x32_bf16 v[30:33], v[158:161], v[198:201], v[30:33]
	v_mfma_f32_16x16x32_bf16 v[22:25], v[150:153], v[210:213], v[22:25]
	v_mfma_f32_16x16x32_bf16 v[14:17], v[158:161], v[210:213], v[14:17]
	v_mfma_f32_16x16x32_bf16 v[6:9], v[150:153], v[218:221], v[6:9]
	v_mfma_f32_16x16x32_bf16 v[2:5], v[158:161], v[218:221], v[2:5]
	s_setprio 0
	s_barrier
	s_add_i32 s63, 0, 0x18000
	s_add_i32 s83, 0, 0x1c000
	v_add_u32_e32 v126, s63, v189
	v_add_u32_e32 v158, s83, v189
	ds_read_b128 v[114:117], v126
	ds_read_b128 v[118:121], v126 offset:1024
	ds_read_b128 v[122:125], v126 offset:2048
	ds_read_b128 v[126:129], v126 offset:3072
	ds_read_b128 v[146:149], v158
	ds_read_b128 v[150:153], v158 offset:1024
	ds_read_b128 v[154:157], v158 offset:2048
	ds_read_b128 v[158:161], v158 offset:3072
	s_add_u32 s80, s80, 0x100000
	s_addc_u32 s81, s81, 0
	s_mov_b32 m0, s89
	v_lshl_add_u64 v[226:227], s[80:81], 0, v[170:171]
	ds_read_b128 v[162:165], v192 offset:32768
	ds_read_b128 v[166:169], v192 offset:33792
	ds_read_b128 v[194:197], v192 offset:34816
	ds_read_b128 v[198:201], v192 offset:35840
	ds_read_b128 v[206:209], v192 offset:36864
	ds_read_b128 v[210:213], v192 offset:37888
	ds_read_b128 v[214:217], v192 offset:38912
	ds_read_b128 v[218:221], v192 offset:39936
	global_load_lds_dwordx4 v[226:227], off
	v_lshl_add_u64 v[226:227], s[80:81], 0, v[174:175]
	s_mov_b32 m0, s90
	s_nop 0
	global_load_lds_dwordx4 v[226:227], off
	s_waitcnt vmcnt(8)
	s_waitcnt lgkmcnt(0)
	s_barrier
	s_setprio 1
	s_waitcnt lgkmcnt(0)
	v_mfma_f32_16x16x32_bf16 v[142:145], v[114:117], v[162:165], v[142:145]
	v_mfma_f32_16x16x32_bf16 v[138:141], v[122:125], v[162:165], v[138:141]
	v_mfma_f32_16x16x32_bf16 v[110:113], v[114:117], v[194:197], v[110:113]
	v_mfma_f32_16x16x32_bf16 v[106:109], v[122:125], v[194:197], v[106:109]
	v_mfma_f32_16x16x32_bf16 v[98:101], v[114:117], v[206:209], v[98:101]
	v_mfma_f32_16x16x32_bf16 v[90:93], v[122:125], v[206:209], v[90:93]
	v_mfma_f32_16x16x32_bf16 v[82:85], v[114:117], v[214:217], v[82:85]
	v_mfma_f32_16x16x32_bf16 v[74:77], v[122:125], v[214:217], v[74:77]
	v_mfma_f32_16x16x32_bf16 v[142:145], v[118:121], v[166:169], v[142:145]
	v_mfma_f32_16x16x32_bf16 v[138:141], v[126:129], v[166:169], v[138:141]
	v_mfma_f32_16x16x32_bf16 v[110:113], v[118:121], v[198:201], v[110:113]
	v_mfma_f32_16x16x32_bf16 v[106:109], v[126:129], v[198:201], v[106:109]
	v_mfma_f32_16x16x32_bf16 v[98:101], v[118:121], v[210:213], v[98:101]
	v_mfma_f32_16x16x32_bf16 v[90:93], v[126:129], v[210:213], v[90:93]
	v_mfma_f32_16x16x32_bf16 v[82:85], v[118:121], v[218:221], v[82:85]
	v_mfma_f32_16x16x32_bf16 v[74:77], v[126:129], v[218:221], v[74:77]
	s_setprio 0
	s_setprio 1
	v_mfma_f32_16x16x32_bf16 v[134:137], v[146:149], v[162:165], v[134:137]
	v_mfma_f32_16x16x32_bf16 v[130:133], v[154:157], v[162:165], v[130:133]
	v_mfma_f32_16x16x32_bf16 v[102:105], v[146:149], v[194:197], v[102:105]
	v_mfma_f32_16x16x32_bf16 v[94:97], v[154:157], v[194:197], v[94:97]
	v_mfma_f32_16x16x32_bf16 v[86:89], v[146:149], v[206:209], v[86:89]
	v_mfma_f32_16x16x32_bf16 v[78:81], v[154:157], v[206:209], v[78:81]
	v_mfma_f32_16x16x32_bf16 v[70:73], v[146:149], v[214:217], v[70:73]
	v_mfma_f32_16x16x32_bf16 v[66:69], v[154:157], v[214:217], v[66:69]
	v_mfma_f32_16x16x32_bf16 v[134:137], v[150:153], v[166:169], v[134:137]
	v_mfma_f32_16x16x32_bf16 v[130:133], v[158:161], v[166:169], v[130:133]
	v_mfma_f32_16x16x32_bf16 v[102:105], v[150:153], v[198:201], v[102:105]
	v_mfma_f32_16x16x32_bf16 v[94:97], v[158:161], v[198:201], v[94:97]
	v_mfma_f32_16x16x32_bf16 v[86:89], v[150:153], v[210:213], v[86:89]
	v_mfma_f32_16x16x32_bf16 v[78:81], v[158:161], v[210:213], v[78:81]
	v_mfma_f32_16x16x32_bf16 v[70:73], v[150:153], v[218:221], v[70:73]
	v_mfma_f32_16x16x32_bf16 v[66:69], v[158:161], v[218:221], v[66:69]
	s_setprio 0
	s_barrier
	s_add_i32 s63, s63, s86
	v_lshl_add_u64 v[186:187], v[186:187], 0, s[22:23]
	s_mov_b32 m0, s63
	ds_read_b128 v[162:165], v192 offset:49152
	ds_read_b128 v[166:169], v192 offset:50176
	ds_read_b128 v[194:197], v192 offset:51200
	ds_read_b128 v[198:201], v192 offset:52224
	ds_read_b128 v[206:209], v192 offset:53248
	ds_read_b128 v[210:213], v192 offset:54272
	ds_read_b128 v[214:217], v192 offset:55296
	ds_read_b128 v[218:221], v192 offset:56320
	global_load_lds_dwordx4 v[186:187], off
	s_add_i32 m0, s63, 0x2000
	s_add_u32 s78, s78, 0x100080
	v_lshl_add_u64 v[186:187], v[202:203], 0, s[22:23]
	s_addc_u32 s79, s79, 0
	s_add_i32 s63, s83, s86
	global_load_lds_dwordx4 v[186:187], off
	v_lshl_add_u64 v[186:187], s[78:79], 0, v[172:173]
	s_mov_b32 m0, s63
	s_nop 0
	global_load_lds_dwordx4 v[186:187], off
	v_lshl_add_u64 v[186:187], s[78:79], 0, v[176:177]
	s_add_i32 m0, s63, 0x2000
	s_nop 0
	global_load_lds_dwordx4 v[186:187], off
	v_lshl_add_u64 v[186:187], v[222:223], 0, s[22:23]
	s_mov_b32 m0, s95
	s_nop 0
	global_load_lds_dwordx4 v[186:187], off
	v_lshl_add_u64 v[186:187], v[224:225], 0, s[22:23]
	s_mov_b32 m0, s96
	s_nop 0
	global_load_lds_dwordx4 v[186:187], off
	s_waitcnt vmcnt(8)
	s_waitcnt lgkmcnt(0)
	s_barrier
	s_setprio 1
	s_waitcnt lgkmcnt(0)
	v_mfma_f32_16x16x32_bf16 v[62:65], v[114:117], v[162:165], v[62:65]
	v_mfma_f32_16x16x32_bf16 v[58:61], v[122:125], v[162:165], v[58:61]
	v_mfma_f32_16x16x32_bf16 v[50:53], v[114:117], v[194:197], v[50:53]
	v_mfma_f32_16x16x32_bf16 v[42:45], v[122:125], v[194:197], v[42:45]
	v_mfma_f32_16x16x32_bf16 v[34:37], v[114:117], v[206:209], v[34:37]
	v_mfma_f32_16x16x32_bf16 v[26:29], v[122:125], v[206:209], v[26:29]
	v_mfma_f32_16x16x32_bf16 v[18:21], v[114:117], v[214:217], v[18:21]
	v_mfma_f32_16x16x32_bf16 v[10:13], v[122:125], v[214:217], v[10:13]
	v_mfma_f32_16x16x32_bf16 v[62:65], v[118:121], v[166:169], v[62:65]
	v_mfma_f32_16x16x32_bf16 v[58:61], v[126:129], v[166:169], v[58:61]
	v_mfma_f32_16x16x32_bf16 v[50:53], v[118:121], v[198:201], v[50:53]
	v_mfma_f32_16x16x32_bf16 v[42:45], v[126:129], v[198:201], v[42:45]
	v_mfma_f32_16x16x32_bf16 v[34:37], v[118:121], v[210:213], v[34:37]
	v_mfma_f32_16x16x32_bf16 v[26:29], v[126:129], v[210:213], v[26:29]
	v_mfma_f32_16x16x32_bf16 v[18:21], v[118:121], v[218:221], v[18:21]
	v_mfma_f32_16x16x32_bf16 v[10:13], v[126:129], v[218:221], v[10:13]
	s_setprio 0
	s_setprio 1
	v_mfma_f32_16x16x32_bf16 v[54:57], v[146:149], v[162:165], v[54:57]
	v_mfma_f32_16x16x32_bf16 v[46:49], v[154:157], v[162:165], v[46:49]
	v_mfma_f32_16x16x32_bf16 v[38:41], v[146:149], v[194:197], v[38:41]
	v_mfma_f32_16x16x32_bf16 v[30:33], v[154:157], v[194:197], v[30:33]
	v_mfma_f32_16x16x32_bf16 v[22:25], v[146:149], v[206:209], v[22:25]
	v_mfma_f32_16x16x32_bf16 v[14:17], v[154:157], v[206:209], v[14:17]
	v_mfma_f32_16x16x32_bf16 v[6:9], v[146:149], v[214:217], v[6:9]
	v_mfma_f32_16x16x32_bf16 v[2:5], v[154:157], v[214:217], v[2:5]
	v_mfma_f32_16x16x32_bf16 v[54:57], v[150:153], v[166:169], v[54:57]
	v_mfma_f32_16x16x32_bf16 v[46:49], v[158:161], v[166:169], v[46:49]
	v_mfma_f32_16x16x32_bf16 v[38:41], v[150:153], v[198:201], v[38:41]
	v_mfma_f32_16x16x32_bf16 v[30:33], v[158:161], v[198:201], v[30:33]
	v_mfma_f32_16x16x32_bf16 v[22:25], v[150:153], v[210:213], v[22:25]
	v_mfma_f32_16x16x32_bf16 v[14:17], v[158:161], v[210:213], v[14:17]
	v_mfma_f32_16x16x32_bf16 v[6:9], v[150:153], v[218:221], v[6:9]
	v_mfma_f32_16x16x32_bf16 v[2:5], v[158:161], v[218:221], v[2:5]
	s_setprio 0
	s_barrier
	s_add_u32 s76, s76, 0x100
	s_addc_u32 s77, s77, 0
	s_add_u32 s47, s47, 0x100
	s_addc_u32 s62, s62, 0
	s_cmp_ge_i32 s82, s7
	s_mov_b32 s63, s82

.LBB0_1012:
	s_add_u32 s48, s96, s44
	s_addc_u32 s49, s97, s45
	s_and_b64 s[14:15], s[4:5], exec
	s_cselect_b32 s6, s49, s65
	s_cselect_b32 s14, s48, s64
	s_add_u32 s50, s3, s46
	s_addc_u32 s51, s35, s47
	s_and_b64 s[18:19], s[4:5], exec
	s_cselect_b32 s15, s51, s67
	s_cselect_b32 s17, s50, s66
	s_add_u32 s64, s64, 0x40080
	s_addc_u32 s65, s65, 0
	s_add_u32 s18, s66, 0x100
	s_addc_u32 s19, s67, 0
	s_mov_b32 s24, -2
	ds_read_b128 v[130:133], v172
	ds_read_b128 v[134:137], v172 offset:1024
	ds_read_b128 v[138:141], v172 offset:2048
	ds_read_b128 v[142:145], v172 offset:3072
	ds_read_b128 v[164:167], v173
	ds_read_b128 v[176:179], v173 offset:1024
	ds_read_b128 v[180:183], v173 offset:2048
	ds_read_b128 v[184:187], v173 offset:3072
	s_add_u32 s25, s64, 0xfffc0080
	s_addc_u32 s28, s65, -1
	s_cmp_eq_u32 s24, 12
	s_cselect_b32 s69, s6, s28
	s_cselect_b32 s68, s14, s25
	s_cselect_b32 s67, s15, s19
	s_cselect_b32 s66, s17, s18
	v_lshl_add_u64 v[168:169], s[64:65], 0, v[156:157]
	s_add_i32 m0, s73, 0xc000
	ds_read_b128 v[188:191], v174
	ds_read_b128 v[192:195], v174 offset:1024
	ds_read_b128 v[196:199], v174 offset:2048
	ds_read_b128 v[200:203], v174 offset:3072
	ds_read_b128 v[206:209], v174 offset:4096
	ds_read_b128 v[210:213], v174 offset:5120
	ds_read_b128 v[214:217], v174 offset:6144
	ds_read_b128 v[218:221], v174 offset:7168
	global_load_lds_dwordx4 v[168:169], off
	v_lshl_add_u64 v[168:169], s[64:65], 0, v[158:159]
	s_add_i32 m0, s73, 0xe000
	s_nop 0
	global_load_lds_dwordx4 v[168:169], off
	s_waitcnt vmcnt(8)
	s_waitcnt lgkmcnt(0)
	s_barrier
	s_setprio 1
	s_waitcnt lgkmcnt(0)
	v_mfma_f32_16x16x32_bf16 v[126:129], v[130:133], v[188:191], 0
	v_mfma_f32_16x16x32_bf16 v[122:125], v[138:141], v[188:191], 0
	v_mfma_f32_16x16x32_bf16 v[110:113], v[130:133], v[196:199], 0
	v_mfma_f32_16x16x32_bf16 v[106:109], v[138:141], v[196:199], 0
	v_mfma_f32_16x16x32_bf16 v[94:97], v[130:133], v[206:209], 0
	v_mfma_f32_16x16x32_bf16 v[90:93], v[138:141], v[206:209], 0
	v_mfma_f32_16x16x32_bf16 v[78:81], v[130:133], v[214:217], 0
	v_mfma_f32_16x16x32_bf16 v[74:77], v[138:141], v[214:217], 0
	v_mfma_f32_16x16x32_bf16 v[126:129], v[134:137], v[192:195], v[126:129]
	v_mfma_f32_16x16x32_bf16 v[122:125], v[142:145], v[192:195], v[122:125]
	v_mfma_f32_16x16x32_bf16 v[110:113], v[134:137], v[200:203], v[110:113]
	v_mfma_f32_16x16x32_bf16 v[106:109], v[142:145], v[200:203], v[106:109]
	v_mfma_f32_16x16x32_bf16 v[94:97], v[134:137], v[210:213], v[94:97]
	v_mfma_f32_16x16x32_bf16 v[90:93], v[142:145], v[210:213], v[90:93]
	v_mfma_f32_16x16x32_bf16 v[78:81], v[134:137], v[218:221], v[78:81]
	v_mfma_f32_16x16x32_bf16 v[74:77], v[142:145], v[218:221], v[74:77]
	s_setprio 0
	s_setprio 1
	v_mfma_f32_16x16x32_bf16 v[118:121], v[164:167], v[188:191], 0
	v_mfma_f32_16x16x32_bf16 v[114:117], v[180:183], v[188:191], 0
	v_mfma_f32_16x16x32_bf16 v[102:105], v[164:167], v[196:199], 0
	v_mfma_f32_16x16x32_bf16 v[98:101], v[180:183], v[196:199], 0
	v_mfma_f32_16x16x32_bf16 v[86:89], v[164:167], v[206:209], 0
	v_mfma_f32_16x16x32_bf16 v[82:85], v[180:183], v[206:209], 0
	v_mfma_f32_16x16x32_bf16 v[70:73], v[164:167], v[214:217], 0
	v_mfma_f32_16x16x32_bf16 v[66:69], v[180:183], v[214:217], 0
	v_mfma_f32_16x16x32_bf16 v[118:121], v[176:179], v[192:195], v[118:121]
	v_mfma_f32_16x16x32_bf16 v[114:117], v[184:187], v[192:195], v[114:117]
	v_mfma_f32_16x16x32_bf16 v[102:105], v[176:179], v[200:203], v[102:105]
	v_mfma_f32_16x16x32_bf16 v[98:101], v[184:187], v[200:203], v[98:101]
	v_mfma_f32_16x16x32_bf16 v[86:89], v[176:179], v[210:213], v[86:89]
	v_mfma_f32_16x16x32_bf16 v[82:85], v[184:187], v[210:213], v[82:85]
	v_mfma_f32_16x16x32_bf16 v[70:73], v[176:179], v[218:221], v[70:73]
	v_mfma_f32_16x16x32_bf16 v[66:69], v[184:187], v[218:221], v[66:69]
	s_setprio 0
	s_barrier
	s_add_i32 s25, s82, s70
	v_lshl_add_u64 v[168:169], s[66:67], 0, v[150:151]
	s_mov_b32 m0, s25
	ds_read_b128 v[188:191], v174 offset:16384
	ds_read_b128 v[192:195], v174 offset:17408
	ds_read_b128 v[196:199], v174 offset:18432
	ds_read_b128 v[200:203], v174 offset:19456
	ds_read_b128 v[206:209], v174 offset:20480
	ds_read_b128 v[210:213], v174 offset:21504
	ds_read_b128 v[214:217], v174 offset:22528
	ds_read_b128 v[218:221], v174 offset:23552
	global_load_lds_dwordx4 v[168:169], off
	s_add_i32 m0, s25, 0x2000
	s_add_u32 s28, s66, 0x40000
	v_lshl_add_u64 v[222:223], s[66:67], 0, v[146:147]
	s_addc_u32 s29, s67, 0
	s_add_i32 s25, s83, s70
	global_load_lds_dwordx4 v[222:223], off
	v_lshl_add_u64 v[224:225], s[28:29], 0, v[150:151]
	s_mov_b32 m0, s25
	v_lshl_add_u64 v[226:227], s[68:69], 0, v[148:149]
	global_load_lds_dwordx4 v[224:225], off
	v_lshl_add_u64 v[224:225], s[28:29], 0, v[146:147]
	s_add_i32 m0, s25, 0x2000
	s_nop 0
	global_load_lds_dwordx4 v[224:225], off
	v_lshl_add_u64 v[224:225], s[68:69], 0, v[152:153]
	s_mov_b32 m0, s73
	s_nop 0
	global_load_lds_dwordx4 v[224:225], off
	s_mov_b32 m0, s74
	s_nop 0
	global_load_lds_dwordx4 v[226:227], off
	s_waitcnt vmcnt(8)
	s_waitcnt lgkmcnt(0)
	s_barrier
	s_setprio 1
	s_waitcnt lgkmcnt(0)
	v_mfma_f32_16x16x32_bf16 v[62:65], v[130:133], v[188:191], 0
	v_mfma_f32_16x16x32_bf16 v[58:61], v[138:141], v[188:191], 0
	v_mfma_f32_16x16x32_bf16 v[46:49], v[130:133], v[196:199], 0
	v_mfma_f32_16x16x32_bf16 v[42:45], v[138:141], v[196:199], 0
	v_mfma_f32_16x16x32_bf16 v[30:33], v[130:133], v[206:209], 0
	v_mfma_f32_16x16x32_bf16 v[26:29], v[138:141], v[206:209], 0
	v_mfma_f32_16x16x32_bf16 v[14:17], v[130:133], v[214:217], 0
	v_mfma_f32_16x16x32_bf16 v[10:13], v[138:141], v[214:217], 0
	v_mfma_f32_16x16x32_bf16 v[62:65], v[134:137], v[192:195], v[62:65]
	v_mfma_f32_16x16x32_bf16 v[58:61], v[142:145], v[192:195], v[58:61]
	v_mfma_f32_16x16x32_bf16 v[46:49], v[134:137], v[200:203], v[46:49]
	v_mfma_f32_16x16x32_bf16 v[42:45], v[142:145], v[200:203], v[42:45]
	v_mfma_f32_16x16x32_bf16 v[30:33], v[134:137], v[210:213], v[30:33]
	v_mfma_f32_16x16x32_bf16 v[26:29], v[142:145], v[210:213], v[26:29]
	v_mfma_f32_16x16x32_bf16 v[14:17], v[134:137], v[218:221], v[14:17]
	v_mfma_f32_16x16x32_bf16 v[10:13], v[142:145], v[218:221], v[10:13]
	s_setprio 0
	s_setprio 1
	v_mfma_f32_16x16x32_bf16 v[54:57], v[164:167], v[188:191], 0
	v_mfma_f32_16x16x32_bf16 v[50:53], v[180:183], v[188:191], 0
	v_mfma_f32_16x16x32_bf16 v[38:41], v[164:167], v[196:199], 0
	v_mfma_f32_16x16x32_bf16 v[34:37], v[180:183], v[196:199], 0
	v_mfma_f32_16x16x32_bf16 v[22:25], v[164:167], v[206:209], 0
	v_mfma_f32_16x16x32_bf16 v[18:21], v[180:183], v[206:209], 0
	v_mfma_f32_16x16x32_bf16 v[6:9], v[164:167], v[214:217], 0
	v_mfma_f32_16x16x32_bf16 v[2:5], v[180:183], v[214:217], 0
	v_mfma_f32_16x16x32_bf16 v[54:57], v[176:179], v[192:195], v[54:57]
	v_mfma_f32_16x16x32_bf16 v[50:53], v[184:187], v[192:195], v[50:53]
	v_mfma_f32_16x16x32_bf16 v[38:41], v[176:179], v[200:203], v[38:41]
	v_mfma_f32_16x16x32_bf16 v[34:37], v[184:187], v[200:203], v[34:37]
	v_mfma_f32_16x16x32_bf16 v[22:25], v[176:179], v[210:213], v[22:25]
	v_mfma_f32_16x16x32_bf16 v[18:21], v[184:187], v[210:213], v[18:21]
	v_mfma_f32_16x16x32_bf16 v[6:9], v[176:179], v[218:221], v[6:9]
	v_mfma_f32_16x16x32_bf16 v[2:5], v[184:187], v[218:221], v[2:5]
	s_setprio 0
	s_barrier
	s_add_i32 s25, 0, 0x18000
	s_add_i32 s30, 0, 0x1c000
	v_add_u32_e32 v142, s25, v171
	v_add_u32_e32 v175, s30, v171
	ds_read_b128 v[130:133], v142
	ds_read_b128 v[134:137], v142 offset:1024
	ds_read_b128 v[138:141], v142 offset:2048
	ds_read_b128 v[142:145], v142 offset:3072
	ds_read_b128 v[164:167], v175
	ds_read_b128 v[176:179], v175 offset:1024
	ds_read_b128 v[180:183], v175 offset:2048
	ds_read_b128 v[184:187], v175 offset:3072
	s_add_u32 s28, s68, 0x40000
	s_addc_u32 s29, s69, 0
	s_mov_b32 m0, s75
	v_lshl_add_u64 v[228:229], s[28:29], 0, v[152:153]
	ds_read_b128 v[188:191], v174 offset:32768
	ds_read_b128 v[192:195], v174 offset:33792
	ds_read_b128 v[196:199], v174 offset:34816
	ds_read_b128 v[200:203], v174 offset:35840
	ds_read_b128 v[206:209], v174 offset:36864
	ds_read_b128 v[210:213], v174 offset:37888
	ds_read_b128 v[214:217], v174 offset:38912
	ds_read_b128 v[218:221], v174 offset:39936
	global_load_lds_dwordx4 v[228:229], off
	v_lshl_add_u64 v[228:229], s[28:29], 0, v[148:149]
	s_mov_b32 m0, s76
	s_nop 0
	global_load_lds_dwordx4 v[228:229], off
	s_waitcnt vmcnt(8)
	s_waitcnt lgkmcnt(0)
	s_barrier
	s_setprio 1
	s_waitcnt lgkmcnt(0)
	v_mfma_f32_16x16x32_bf16 v[126:129], v[130:133], v[188:191], v[126:129]
	v_mfma_f32_16x16x32_bf16 v[122:125], v[138:141], v[188:191], v[122:125]
	v_mfma_f32_16x16x32_bf16 v[110:113], v[130:133], v[196:199], v[110:113]
	v_mfma_f32_16x16x32_bf16 v[106:109], v[138:141], v[196:199], v[106:109]
	v_mfma_f32_16x16x32_bf16 v[94:97], v[130:133], v[206:209], v[94:97]
	v_mfma_f32_16x16x32_bf16 v[90:93], v[138:141], v[206:209], v[90:93]
	v_mfma_f32_16x16x32_bf16 v[78:81], v[130:133], v[214:217], v[78:81]
	v_mfma_f32_16x16x32_bf16 v[74:77], v[138:141], v[214:217], v[74:77]
	v_mfma_f32_16x16x32_bf16 v[126:129], v[134:137], v[192:195], v[126:129]
	v_mfma_f32_16x16x32_bf16 v[122:125], v[142:145], v[192:195], v[122:125]
	v_mfma_f32_16x16x32_bf16 v[110:113], v[134:137], v[200:203], v[110:113]
	v_mfma_f32_16x16x32_bf16 v[106:109], v[142:145], v[200:203], v[106:109]
	v_mfma_f32_16x16x32_bf16 v[94:97], v[134:137], v[210:213], v[94:97]
	v_mfma_f32_16x16x32_bf16 v[90:93], v[142:145], v[210:213], v[90:93]
	v_mfma_f32_16x16x32_bf16 v[78:81], v[134:137], v[218:221], v[78:81]
	v_mfma_f32_16x16x32_bf16 v[74:77], v[142:145], v[218:221], v[74:77]
	s_setprio 0
	s_setprio 1
	v_mfma_f32_16x16x32_bf16 v[118:121], v[164:167], v[188:191], v[118:121]
	v_mfma_f32_16x16x32_bf16 v[114:117], v[180:183], v[188:191], v[114:117]
	v_mfma_f32_16x16x32_bf16 v[102:105], v[164:167], v[196:199], v[102:105]
	v_mfma_f32_16x16x32_bf16 v[98:101], v[180:183], v[196:199], v[98:101]
	v_mfma_f32_16x16x32_bf16 v[86:89], v[164:167], v[206:209], v[86:89]
	v_mfma_f32_16x16x32_bf16 v[82:85], v[180:183], v[206:209], v[82:85]
	v_mfma_f32_16x16x32_bf16 v[70:73], v[164:167], v[214:217], v[70:73]
	v_mfma_f32_16x16x32_bf16 v[66:69], v[180:183], v[214:217], v[66:69]
	v_mfma_f32_16x16x32_bf16 v[118:121], v[176:179], v[192:195], v[118:121]
	v_mfma_f32_16x16x32_bf16 v[114:117], v[184:187], v[192:195], v[114:117]
	v_mfma_f32_16x16x32_bf16 v[102:105], v[176:179], v[200:203], v[102:105]
	v_mfma_f32_16x16x32_bf16 v[98:101], v[184:187], v[200:203], v[98:101]
	v_mfma_f32_16x16x32_bf16 v[86:89], v[176:179], v[210:213], v[86:89]
	v_mfma_f32_16x16x32_bf16 v[82:85], v[184:187], v[210:213], v[82:85]
	v_mfma_f32_16x16x32_bf16 v[70:73], v[176:179], v[218:221], v[70:73]
	v_mfma_f32_16x16x32_bf16 v[66:69], v[184:187], v[218:221], v[66:69]
	s_setprio 0
	s_barrier
	s_add_i32 s25, s25, s70
	v_lshl_add_u64 v[168:169], v[168:169], 0, s[36:37]
	s_mov_b32 m0, s25
	ds_read_b128 v[188:191], v174 offset:49152
	ds_read_b128 v[192:195], v174 offset:50176
	ds_read_b128 v[196:199], v174 offset:51200
	ds_read_b128 v[200:203], v174 offset:52224
	ds_read_b128 v[206:209], v174 offset:53248
	ds_read_b128 v[210:213], v174 offset:54272
	ds_read_b128 v[214:217], v174 offset:55296
	ds_read_b128 v[218:221], v174 offset:56320
	global_load_lds_dwordx4 v[168:169], off
	s_add_i32 m0, s25, 0x2000
	s_add_u32 s28, s66, 0x40080
	v_lshl_add_u64 v[168:169], v[222:223], 0, s[36:37]
	s_addc_u32 s29, s67, 0
	s_add_i32 s25, s30, s70
	global_load_lds_dwordx4 v[168:169], off
	v_lshl_add_u64 v[168:169], s[28:29], 0, v[150:151]
	s_mov_b32 m0, s25
	s_nop 0
	global_load_lds_dwordx4 v[168:169], off
	v_lshl_add_u64 v[168:169], s[28:29], 0, v[146:147]
	s_add_i32 m0, s25, 0x2000
	s_nop 0
	global_load_lds_dwordx4 v[168:169], off
	v_lshl_add_u64 v[168:169], v[224:225], 0, s[36:37]
	s_mov_b32 m0, s79
	s_nop 0
	global_load_lds_dwordx4 v[168:169], off
	v_lshl_add_u64 v[168:169], v[226:227], 0, s[36:37]
	s_mov_b32 m0, s80
	s_nop 0
	global_load_lds_dwordx4 v[168:169], off
	s_waitcnt vmcnt(8)
	s_waitcnt lgkmcnt(0)
	s_barrier
	s_setprio 1
	s_waitcnt lgkmcnt(0)
	v_mfma_f32_16x16x32_bf16 v[62:65], v[130:133], v[188:191], v[62:65]
	v_mfma_f32_16x16x32_bf16 v[58:61], v[138:141], v[188:191], v[58:61]
	v_mfma_f32_16x16x32_bf16 v[46:49], v[130:133], v[196:199], v[46:49]
	v_mfma_f32_16x16x32_bf16 v[42:45], v[138:141], v[196:199], v[42:45]
	v_mfma_f32_16x16x32_bf16 v[30:33], v[130:133], v[206:209], v[30:33]
	v_mfma_f32_16x16x32_bf16 v[26:29], v[138:141], v[206:209], v[26:29]
	v_mfma_f32_16x16x32_bf16 v[14:17], v[130:133], v[214:217], v[14:17]
	v_mfma_f32_16x16x32_bf16 v[10:13], v[138:141], v[214:217], v[10:13]
	v_mfma_f32_16x16x32_bf16 v[62:65], v[134:137], v[192:195], v[62:65]
	v_mfma_f32_16x16x32_bf16 v[58:61], v[142:145], v[192:195], v[58:61]
	v_mfma_f32_16x16x32_bf16 v[46:49], v[134:137], v[200:203], v[46:49]
	v_mfma_f32_16x16x32_bf16 v[42:45], v[142:145], v[200:203], v[42:45]
	v_mfma_f32_16x16x32_bf16 v[30:33], v[134:137], v[210:213], v[30:33]
	v_mfma_f32_16x16x32_bf16 v[26:29], v[142:145], v[210:213], v[26:29]
	v_mfma_f32_16x16x32_bf16 v[14:17], v[134:137], v[218:221], v[14:17]
	v_mfma_f32_16x16x32_bf16 v[10:13], v[142:145], v[218:221], v[10:13]
	s_setprio 0
	s_setprio 1
	v_mfma_f32_16x16x32_bf16 v[54:57], v[164:167], v[188:191], v[54:57]
	v_mfma_f32_16x16x32_bf16 v[50:53], v[180:183], v[188:191], v[50:53]
	v_mfma_f32_16x16x32_bf16 v[38:41], v[164:167], v[196:199], v[38:41]
	v_mfma_f32_16x16x32_bf16 v[34:37], v[180:183], v[196:199], v[34:37]
	v_mfma_f32_16x16x32_bf16 v[22:25], v[164:167], v[206:209], v[22:25]
	v_mfma_f32_16x16x32_bf16 v[18:21], v[180:183], v[206:209], v[18:21]
	v_mfma_f32_16x16x32_bf16 v[6:9], v[164:167], v[214:217], v[6:9]
	v_mfma_f32_16x16x32_bf16 v[2:5], v[180:183], v[214:217], v[2:5]
	v_mfma_f32_16x16x32_bf16 v[54:57], v[176:179], v[192:195], v[54:57]
	v_mfma_f32_16x16x32_bf16 v[50:53], v[184:187], v[192:195], v[50:53]
	v_mfma_f32_16x16x32_bf16 v[38:41], v[176:179], v[200:203], v[38:41]
	v_mfma_f32_16x16x32_bf16 v[34:37], v[184:187], v[200:203], v[34:37]
	v_mfma_f32_16x16x32_bf16 v[22:25], v[176:179], v[210:213], v[22:25]
	v_mfma_f32_16x16x32_bf16 v[18:21], v[184:187], v[210:213], v[18:21]
	v_mfma_f32_16x16x32_bf16 v[6:9], v[176:179], v[218:221], v[6:9]
	v_mfma_f32_16x16x32_bf16 v[2:5], v[184:187], v[218:221], v[2:5]
	s_setprio 0
	s_barrier
	s_add_i32 s24, s24, 2
	s_add_u32 s64, s64, 0x100
	s_addc_u32 s65, s65, 0
	s_add_u32 s18, s18, 0x100
	s_addc_u32 s19, s19, 0
	s_cmp_gt_u32 s24, 13

.LBB0_1427:
	s_add_u32 s90, s35, s86
	s_addc_u32 s91, s64, s87
	s_and_b64 s[14:15], s[88:89], exec
	s_cselect_b32 s14, s91, s11
	s_cselect_b32 s15, s90, s10
	s_add_u32 s92, s65, s74
	s_addc_u32 s93, s68, s75
	s_and_b64 s[66:67], s[88:89], exec
	s_cselect_b32 s51, s93, s95
	s_cselect_b32 s84, s92, s94
	s_add_i32 s85, s18, -2
	s_add_u32 s10, s10, 0x40080
	s_addc_u32 s11, s11, 0
	s_add_u32 vcc_lo, s94, 0x100
	s_addc_u32 vcc_hi, s95, 0
	s_mov_b32 s94, 0
	s_add_i32 s66, s94, 2
	s_add_u32 s67, s10, 0xfffc0080
	s_addc_u32 s72, s11, -1
	s_cmp_eq_u32 s85, s94
	s_cselect_b32 s97, s14, s72
	s_cselect_b32 s96, s15, s67
	s_cselect_b32 s95, s51, vcc_hi
	s_cselect_b32 s94, s84, vcc_lo
	s_add_i32 s67, 0, 0x10000
	s_add_i32 s62, 0, 0x14000
	v_add_u32_e32 v126, s67, v199
	v_add_u32_e32 v158, s62, v199
	ds_read_b128 v[114:117], v126
	ds_read_b128 v[118:121], v126 offset:1024
	ds_read_b128 v[122:125], v126 offset:2048
	ds_read_b128 v[126:129], v126 offset:3072
	ds_read_b128 v[146:149], v158
	ds_read_b128 v[150:153], v158 offset:1024
	ds_read_b128 v[154:157], v158 offset:2048
	ds_read_b128 v[158:161], v158 offset:3072
	v_lshl_add_u64 v[202:203], s[10:11], 0, v[196:197]
	s_add_i32 m0, s28, 0xc000
	ds_read_b128 v[162:165], v214
	ds_read_b128 v[166:169], v214 offset:1024
	ds_read_b128 v[216:219], v214 offset:2048
	ds_read_b128 v[220:223], v214 offset:3072
	ds_read_b128 v[224:227], v214 offset:4096
	ds_read_b128 v[228:231], v214 offset:5120
	ds_read_b128 v[232:235], v214 offset:6144
	ds_read_b128 v[236:239], v214 offset:7168
	global_load_lds_dwordx4 v[202:203], off
	v_lshl_add_u64 v[202:203], s[10:11], 0, v[176:177]
	s_add_i32 m0, s28, 0xe000
	s_nop 0
	global_load_lds_dwordx4 v[202:203], off
	s_waitcnt vmcnt(8)
	s_waitcnt lgkmcnt(0)
	s_barrier
	s_setprio 1
	s_waitcnt lgkmcnt(0)
	v_mfma_f32_16x16x32_bf16 v[142:145], v[114:117], v[162:165], 0
	v_mfma_f32_16x16x32_bf16 v[138:141], v[122:125], v[162:165], 0
	v_mfma_f32_16x16x32_bf16 v[110:113], v[114:117], v[216:219], 0
	v_mfma_f32_16x16x32_bf16 v[106:109], v[122:125], v[216:219], 0
	v_mfma_f32_16x16x32_bf16 v[98:101], v[114:117], v[224:227], 0
	v_mfma_f32_16x16x32_bf16 v[90:93], v[122:125], v[224:227], 0
	v_mfma_f32_16x16x32_bf16 v[82:85], v[114:117], v[232:235], 0
	v_mfma_f32_16x16x32_bf16 v[74:77], v[122:125], v[232:235], 0
	v_mfma_f32_16x16x32_bf16 v[142:145], v[118:121], v[166:169], v[142:145]
	v_mfma_f32_16x16x32_bf16 v[138:141], v[126:129], v[166:169], v[138:141]
	v_mfma_f32_16x16x32_bf16 v[110:113], v[118:121], v[220:223], v[110:113]
	v_mfma_f32_16x16x32_bf16 v[106:109], v[126:129], v[220:223], v[106:109]
	v_mfma_f32_16x16x32_bf16 v[98:101], v[118:121], v[228:231], v[98:101]
	v_mfma_f32_16x16x32_bf16 v[90:93], v[126:129], v[228:231], v[90:93]
	v_mfma_f32_16x16x32_bf16 v[82:85], v[118:121], v[236:239], v[82:85]
	v_mfma_f32_16x16x32_bf16 v[74:77], v[126:129], v[236:239], v[74:77]
	s_setprio 0
	s_setprio 1
	v_mfma_f32_16x16x32_bf16 v[134:137], v[146:149], v[162:165], 0
	v_mfma_f32_16x16x32_bf16 v[130:133], v[154:157], v[162:165], 0
	v_mfma_f32_16x16x32_bf16 v[102:105], v[146:149], v[216:219], 0
	v_mfma_f32_16x16x32_bf16 v[94:97], v[154:157], v[216:219], 0
	v_mfma_f32_16x16x32_bf16 v[86:89], v[146:149], v[224:227], 0
	v_mfma_f32_16x16x32_bf16 v[78:81], v[154:157], v[224:227], 0
	v_mfma_f32_16x16x32_bf16 v[70:73], v[146:149], v[232:235], 0
	v_mfma_f32_16x16x32_bf16 v[66:69], v[154:157], v[232:235], 0
	v_mfma_f32_16x16x32_bf16 v[134:137], v[150:153], v[166:169], v[134:137]
	v_mfma_f32_16x16x32_bf16 v[130:133], v[158:161], v[166:169], v[130:133]
	v_mfma_f32_16x16x32_bf16 v[102:105], v[150:153], v[220:223], v[102:105]
	v_mfma_f32_16x16x32_bf16 v[94:97], v[158:161], v[220:223], v[94:97]
	v_mfma_f32_16x16x32_bf16 v[86:89], v[150:153], v[228:231], v[86:89]
	v_mfma_f32_16x16x32_bf16 v[78:81], v[158:161], v[228:231], v[78:81]
	v_mfma_f32_16x16x32_bf16 v[70:73], v[150:153], v[236:239], v[70:73]
	v_mfma_f32_16x16x32_bf16 v[66:69], v[158:161], v[236:239], v[66:69]
	s_setprio 0
	s_barrier
	s_add_i32 s63, s67, s17
	v_lshl_add_u64 v[202:203], s[94:95], 0, v[174:175]
	s_mov_b32 m0, s63
	ds_read_b128 v[162:165], v214 offset:16384
	ds_read_b128 v[166:169], v214 offset:17408
	ds_read_b128 v[216:219], v214 offset:18432
	ds_read_b128 v[220:223], v214 offset:19456
	ds_read_b128 v[224:227], v214 offset:20480
	ds_read_b128 v[228:231], v214 offset:21504
	ds_read_b128 v[232:235], v214 offset:22528
	ds_read_b128 v[236:239], v214 offset:23552
	global_load_lds_dwordx4 v[202:203], off
	s_add_i32 m0, s63, 0x2000
	s_add_u32 s72, s94, 0x40000
	v_lshl_add_u64 v[240:241], s[94:95], 0, v[178:179]
	s_addc_u32 s73, s95, 0
	s_add_i32 s62, s62, s17
	global_load_lds_dwordx4 v[240:241], off
	v_lshl_add_u64 v[242:243], s[72:73], 0, v[174:175]
	s_mov_b32 m0, s62
	v_lshl_add_u64 v[244:245], s[96:97], 0, v[176:177]
	global_load_lds_dwordx4 v[242:243], off
	v_lshl_add_u64 v[242:243], s[72:73], 0, v[178:179]
	s_add_i32 m0, s62, 0x2000
	s_nop 0
	global_load_lds_dwordx4 v[242:243], off
	v_lshl_add_u64 v[242:243], s[96:97], 0, v[172:173]
	s_mov_b32 m0, s28
	s_nop 0
	global_load_lds_dwordx4 v[242:243], off
	s_mov_b32 m0, s29
	s_nop 0
	global_load_lds_dwordx4 v[244:245], off
	s_waitcnt vmcnt(8)
	s_waitcnt lgkmcnt(0)
	s_barrier
	s_setprio 1
	s_waitcnt lgkmcnt(0)
	v_mfma_f32_16x16x32_bf16 v[62:65], v[114:117], v[162:165], 0
	v_mfma_f32_16x16x32_bf16 v[58:61], v[122:125], v[162:165], 0
	v_mfma_f32_16x16x32_bf16 v[50:53], v[114:117], v[216:219], 0
	v_mfma_f32_16x16x32_bf16 v[42:45], v[122:125], v[216:219], 0
	v_mfma_f32_16x16x32_bf16 v[34:37], v[114:117], v[224:227], 0
	v_mfma_f32_16x16x32_bf16 v[26:29], v[122:125], v[224:227], 0
	v_mfma_f32_16x16x32_bf16 v[18:21], v[114:117], v[232:235], 0
	v_mfma_f32_16x16x32_bf16 v[10:13], v[122:125], v[232:235], 0
	v_mfma_f32_16x16x32_bf16 v[62:65], v[118:121], v[166:169], v[62:65]
	v_mfma_f32_16x16x32_bf16 v[58:61], v[126:129], v[166:169], v[58:61]
	v_mfma_f32_16x16x32_bf16 v[50:53], v[118:121], v[220:223], v[50:53]
	v_mfma_f32_16x16x32_bf16 v[42:45], v[126:129], v[220:223], v[42:45]
	v_mfma_f32_16x16x32_bf16 v[34:37], v[118:121], v[228:231], v[34:37]
	v_mfma_f32_16x16x32_bf16 v[26:29], v[126:129], v[228:231], v[26:29]
	v_mfma_f32_16x16x32_bf16 v[18:21], v[118:121], v[236:239], v[18:21]
	v_mfma_f32_16x16x32_bf16 v[10:13], v[126:129], v[236:239], v[10:13]
	s_setprio 0
	s_setprio 1
	v_mfma_f32_16x16x32_bf16 v[54:57], v[146:149], v[162:165], 0
	v_mfma_f32_16x16x32_bf16 v[46:49], v[154:157], v[162:165], 0
	v_mfma_f32_16x16x32_bf16 v[38:41], v[146:149], v[216:219], 0
	v_mfma_f32_16x16x32_bf16 v[30:33], v[154:157], v[216:219], 0
	v_mfma_f32_16x16x32_bf16 v[22:25], v[146:149], v[224:227], 0
	v_mfma_f32_16x16x32_bf16 v[14:17], v[154:157], v[224:227], 0
	v_mfma_f32_16x16x32_bf16 v[6:9], v[146:149], v[232:235], 0
	v_mfma_f32_16x16x32_bf16 v[2:5], v[154:157], v[232:235], 0
	v_mfma_f32_16x16x32_bf16 v[54:57], v[150:153], v[166:169], v[54:57]
	v_mfma_f32_16x16x32_bf16 v[46:49], v[158:161], v[166:169], v[46:49]
	v_mfma_f32_16x16x32_bf16 v[38:41], v[150:153], v[220:223], v[38:41]
	v_mfma_f32_16x16x32_bf16 v[30:33], v[158:161], v[220:223], v[30:33]
	v_mfma_f32_16x16x32_bf16 v[22:25], v[150:153], v[228:231], v[22:25]
	v_mfma_f32_16x16x32_bf16 v[14:17], v[158:161], v[228:231], v[14:17]
	v_mfma_f32_16x16x32_bf16 v[6:9], v[150:153], v[236:239], v[6:9]
	v_mfma_f32_16x16x32_bf16 v[2:5], v[158:161], v[236:239], v[2:5]
	s_setprio 0
	s_barrier
	s_add_i32 s62, 0, 0x18000
	s_add_i32 s63, 0, 0x1c000
	v_add_u32_e32 v126, s62, v199
	v_add_u32_e32 v158, s63, v199
	ds_read_b128 v[114:117], v126
	ds_read_b128 v[118:121], v126 offset:1024
	ds_read_b128 v[122:125], v126 offset:2048
	ds_read_b128 v[126:129], v126 offset:3072
	ds_read_b128 v[146:149], v158
	ds_read_b128 v[150:153], v158 offset:1024
	ds_read_b128 v[154:157], v158 offset:2048
	ds_read_b128 v[158:161], v158 offset:3072
	s_add_u32 s72, s96, 0x40000
	s_addc_u32 s73, s97, 0
	s_mov_b32 m0, s30
	v_lshl_add_u64 v[246:247], s[72:73], 0, v[172:173]
	ds_read_b128 v[162:165], v214 offset:32768
	ds_read_b128 v[166:169], v214 offset:33792
	ds_read_b128 v[216:219], v214 offset:34816
	ds_read_b128 v[220:223], v214 offset:35840
	ds_read_b128 v[224:227], v214 offset:36864
	ds_read_b128 v[228:231], v214 offset:37888
	ds_read_b128 v[232:235], v214 offset:38912
	ds_read_b128 v[236:239], v214 offset:39936
	global_load_lds_dwordx4 v[246:247], off
	v_lshl_add_u64 v[246:247], s[72:73], 0, v[176:177]
	s_mov_b32 m0, s31
	s_nop 0
	global_load_lds_dwordx4 v[246:247], off
	s_waitcnt vmcnt(8)
	s_waitcnt lgkmcnt(0)
	s_barrier
	s_setprio 1
	s_waitcnt lgkmcnt(0)
	v_mfma_f32_16x16x32_bf16 v[142:145], v[114:117], v[162:165], v[142:145]
	v_mfma_f32_16x16x32_bf16 v[138:141], v[122:125], v[162:165], v[138:141]
	v_mfma_f32_16x16x32_bf16 v[110:113], v[114:117], v[216:219], v[110:113]
	v_mfma_f32_16x16x32_bf16 v[106:109], v[122:125], v[216:219], v[106:109]
	v_mfma_f32_16x16x32_bf16 v[98:101], v[114:117], v[224:227], v[98:101]
	v_mfma_f32_16x16x32_bf16 v[90:93], v[122:125], v[224:227], v[90:93]
	v_mfma_f32_16x16x32_bf16 v[82:85], v[114:117], v[232:235], v[82:85]
	v_mfma_f32_16x16x32_bf16 v[74:77], v[122:125], v[232:235], v[74:77]
	v_mfma_f32_16x16x32_bf16 v[142:145], v[118:121], v[166:169], v[142:145]
	v_mfma_f32_16x16x32_bf16 v[138:141], v[126:129], v[166:169], v[138:141]
	v_mfma_f32_16x16x32_bf16 v[110:113], v[118:121], v[220:223], v[110:113]
	v_mfma_f32_16x16x32_bf16 v[106:109], v[126:129], v[220:223], v[106:109]
	v_mfma_f32_16x16x32_bf16 v[98:101], v[118:121], v[228:231], v[98:101]
	v_mfma_f32_16x16x32_bf16 v[90:93], v[126:129], v[228:231], v[90:93]
	v_mfma_f32_16x16x32_bf16 v[82:85], v[118:121], v[236:239], v[82:85]
	v_mfma_f32_16x16x32_bf16 v[74:77], v[126:129], v[236:239], v[74:77]
	s_setprio 0
	s_setprio 1
	v_mfma_f32_16x16x32_bf16 v[134:137], v[146:149], v[162:165], v[134:137]
	v_mfma_f32_16x16x32_bf16 v[130:133], v[154:157], v[162:165], v[130:133]
	v_mfma_f32_16x16x32_bf16 v[102:105], v[146:149], v[216:219], v[102:105]
	v_mfma_f32_16x16x32_bf16 v[94:97], v[154:157], v[216:219], v[94:97]
	v_mfma_f32_16x16x32_bf16 v[86:89], v[146:149], v[224:227], v[86:89]
	v_mfma_f32_16x16x32_bf16 v[78:81], v[154:157], v[224:227], v[78:81]
	v_mfma_f32_16x16x32_bf16 v[70:73], v[146:149], v[232:235], v[70:73]
	v_mfma_f32_16x16x32_bf16 v[66:69], v[154:157], v[232:235], v[66:69]
	v_mfma_f32_16x16x32_bf16 v[134:137], v[150:153], v[166:169], v[134:137]
	v_mfma_f32_16x16x32_bf16 v[130:133], v[158:161], v[166:169], v[130:133]
	v_mfma_f32_16x16x32_bf16 v[102:105], v[150:153], v[220:223], v[102:105]
	v_mfma_f32_16x16x32_bf16 v[94:97], v[158:161], v[220:223], v[94:97]
	v_mfma_f32_16x16x32_bf16 v[86:89], v[150:153], v[228:231], v[86:89]
	v_mfma_f32_16x16x32_bf16 v[78:81], v[158:161], v[228:231], v[78:81]
	v_mfma_f32_16x16x32_bf16 v[70:73], v[150:153], v[236:239], v[70:73]
	v_mfma_f32_16x16x32_bf16 v[66:69], v[158:161], v[236:239], v[66:69]
	s_setprio 0
	s_barrier
	s_add_i32 s62, s62, s17
	v_lshl_add_u64 v[202:203], v[202:203], 0, s[76:77]
	s_mov_b32 m0, s62
	ds_read_b128 v[162:165], v214 offset:49152
	ds_read_b128 v[166:169], v214 offset:50176
	ds_read_b128 v[216:219], v214 offset:51200
	ds_read_b128 v[220:223], v214 offset:52224
	ds_read_b128 v[224:227], v214 offset:53248
	ds_read_b128 v[228:231], v214 offset:54272
	ds_read_b128 v[232:235], v214 offset:55296
	ds_read_b128 v[236:239], v214 offset:56320
	global_load_lds_dwordx4 v[202:203], off
	s_add_i32 m0, s62, 0x2000
	s_add_u32 s72, s94, 0x40080
	v_lshl_add_u64 v[202:203], v[240:241], 0, s[76:77]
	s_addc_u32 s73, s95, 0
	s_add_i32 s62, s63, s17
	global_load_lds_dwordx4 v[202:203], off
	v_lshl_add_u64 v[202:203], s[72:73], 0, v[174:175]
	s_mov_b32 m0, s62
	s_nop 0
	global_load_lds_dwordx4 v[202:203], off
	v_lshl_add_u64 v[202:203], s[72:73], 0, v[178:179]
	s_add_i32 m0, s62, 0x2000
	s_nop 0
	global_load_lds_dwordx4 v[202:203], off
	v_lshl_add_u64 v[202:203], v[242:243], 0, s[76:77]
	s_mov_b32 m0, s44
	s_nop 0
	global_load_lds_dwordx4 v[202:203], off
	v_lshl_add_u64 v[202:203], v[244:245], 0, s[76:77]
	s_mov_b32 m0, s36
	s_nop 0
	global_load_lds_dwordx4 v[202:203], off
	s_waitcnt vmcnt(8)
	s_waitcnt lgkmcnt(0)
	s_barrier
	s_setprio 1
	s_waitcnt lgkmcnt(0)
	v_mfma_f32_16x16x32_bf16 v[62:65], v[114:117], v[162:165], v[62:65]
	v_mfma_f32_16x16x32_bf16 v[58:61], v[122:125], v[162:165], v[58:61]
	v_mfma_f32_16x16x32_bf16 v[50:53], v[114:117], v[216:219], v[50:53]
	v_mfma_f32_16x16x32_bf16 v[42:45], v[122:125], v[216:219], v[42:45]
	v_mfma_f32_16x16x32_bf16 v[34:37], v[114:117], v[224:227], v[34:37]
	v_mfma_f32_16x16x32_bf16 v[26:29], v[122:125], v[224:227], v[26:29]
	v_mfma_f32_16x16x32_bf16 v[18:21], v[114:117], v[232:235], v[18:21]
	v_mfma_f32_16x16x32_bf16 v[10:13], v[122:125], v[232:235], v[10:13]
	v_mfma_f32_16x16x32_bf16 v[62:65], v[118:121], v[166:169], v[62:65]
	v_mfma_f32_16x16x32_bf16 v[58:61], v[126:129], v[166:169], v[58:61]
	v_mfma_f32_16x16x32_bf16 v[50:53], v[118:121], v[220:223], v[50:53]
	v_mfma_f32_16x16x32_bf16 v[42:45], v[126:129], v[220:223], v[42:45]
	v_mfma_f32_16x16x32_bf16 v[34:37], v[118:121], v[228:231], v[34:37]
	v_mfma_f32_16x16x32_bf16 v[26:29], v[126:129], v[228:231], v[26:29]
	v_mfma_f32_16x16x32_bf16 v[18:21], v[118:121], v[236:239], v[18:21]
	v_mfma_f32_16x16x32_bf16 v[10:13], v[126:129], v[236:239], v[10:13]
	s_setprio 0
	s_setprio 1
	v_mfma_f32_16x16x32_bf16 v[54:57], v[146:149], v[162:165], v[54:57]
	v_mfma_f32_16x16x32_bf16 v[46:49], v[154:157], v[162:165], v[46:49]
	v_mfma_f32_16x16x32_bf16 v[38:41], v[146:149], v[216:219], v[38:41]
	v_mfma_f32_16x16x32_bf16 v[30:33], v[154:157], v[216:219], v[30:33]
	v_mfma_f32_16x16x32_bf16 v[22:25], v[146:149], v[224:227], v[22:25]
	v_mfma_f32_16x16x32_bf16 v[14:17], v[154:157], v[224:227], v[14:17]
	v_mfma_f32_16x16x32_bf16 v[6:9], v[146:149], v[232:235], v[6:9]
	v_mfma_f32_16x16x32_bf16 v[2:5], v[154:157], v[232:235], v[2:5]
	v_mfma_f32_16x16x32_bf16 v[54:57], v[150:153], v[166:169], v[54:57]
	v_mfma_f32_16x16x32_bf16 v[46:49], v[158:161], v[166:169], v[46:49]
	v_mfma_f32_16x16x32_bf16 v[38:41], v[150:153], v[220:223], v[38:41]
	v_mfma_f32_16x16x32_bf16 v[30:33], v[158:161], v[220:223], v[30:33]
	v_mfma_f32_16x16x32_bf16 v[22:25], v[150:153], v[228:231], v[22:25]
	v_mfma_f32_16x16x32_bf16 v[14:17], v[158:161], v[228:231], v[14:17]
	v_mfma_f32_16x16x32_bf16 v[6:9], v[150:153], v[236:239], v[6:9]
	v_mfma_f32_16x16x32_bf16 v[2:5], v[158:161], v[236:239], v[2:5]
	s_setprio 0
	s_barrier
	s_add_u32 s10, s10, 0x100
	s_addc_u32 s11, s11, 0
	s_add_u32 vcc_lo, vcc_lo, 0x100
	s_addc_u32 vcc_hi, vcc_hi, 0
	s_cmp_ge_i32 s66, s18
	s_mov_b32 s94, s66

.LBB0_1707:
	v_readlane_b32 s46, v249, 32
	v_readlane_b32 s47, v249, 33
	s_add_u32 s46, s46, s42
	s_addc_u32 s47, s47, s43
	s_and_b64 s[48:49], s[44:45], exec
	s_cselect_b32 s34, s47, s51
	s_cselect_b32 s66, s46, s50
	s_add_u32 s48, s35, s40
	s_addc_u32 s49, s70, s41
	s_and_b64 s[64:65], s[44:45], exec
	s_cselect_b32 s67, s49, s63
	s_cselect_b32 s68, s48, s62
	s_add_i32 s69, s7, -2
	s_add_u32 s50, s50, 0x100080
	s_addc_u32 s51, s51, 0
	s_add_u32 s91, s62, 0x100
	s_addc_u32 s92, s63, 0
	s_mov_b32 s62, 0
	ds_read_b128 v[130:133], v168
	ds_read_b128 v[134:137], v168 offset:1024
	ds_read_b128 v[138:141], v168 offset:2048
	ds_read_b128 v[142:145], v168 offset:3072
	ds_read_b128 v[162:165], v169
	ds_read_b128 v[172:175], v169 offset:1024
	ds_read_b128 v[176:179], v169 offset:2048
	ds_read_b128 v[180:183], v169 offset:3072
	s_add_i32 s93, s62, 2
	s_add_u32 s63, s50, 0xfff00080
	s_addc_u32 s64, s51, -1
	s_cmp_eq_u32 s69, s62
	s_cselect_b32 s62, s68, s91
	s_cselect_b32 s65, s34, s64
	s_cselect_b32 s64, s66, s63
	s_cselect_b32 s63, s67, s92
	v_lshl_add_u64 v[218:219], s[50:51], 0, v[156:157]
	s_add_i32 m0, s12, 0xc000
	ds_read_b128 v[184:187], v170
	ds_read_b128 v[188:191], v170 offset:1024
	ds_read_b128 v[192:195], v170 offset:2048
	ds_read_b128 v[196:199], v170 offset:3072
	ds_read_b128 v[200:203], v170 offset:4096
	ds_read_b128 v[206:209], v170 offset:5120
	ds_read_b128 v[210:213], v170 offset:6144
	ds_read_b128 v[214:217], v170 offset:7168
	global_load_lds_dwordx4 v[218:219], off
	v_lshl_add_u64 v[218:219], s[50:51], 0, v[158:159]
	s_add_i32 m0, s12, 0xe000
	s_nop 0
	global_load_lds_dwordx4 v[218:219], off
	s_waitcnt vmcnt(8)
	s_waitcnt lgkmcnt(0)
	s_barrier
	s_setprio 1
	s_waitcnt lgkmcnt(0)
	v_mfma_f32_16x16x32_bf16 v[126:129], v[130:133], v[184:187], 0
	v_mfma_f32_16x16x32_bf16 v[122:125], v[138:141], v[184:187], 0
	v_mfma_f32_16x16x32_bf16 v[110:113], v[130:133], v[192:195], 0
	v_mfma_f32_16x16x32_bf16 v[106:109], v[138:141], v[192:195], 0
	v_mfma_f32_16x16x32_bf16 v[98:101], v[130:133], v[200:203], 0
	v_mfma_f32_16x16x32_bf16 v[90:93], v[138:141], v[200:203], 0
	v_mfma_f32_16x16x32_bf16 v[82:85], v[130:133], v[210:213], 0
	v_mfma_f32_16x16x32_bf16 v[74:77], v[138:141], v[210:213], 0
	v_mfma_f32_16x16x32_bf16 v[126:129], v[134:137], v[188:191], v[126:129]
	v_mfma_f32_16x16x32_bf16 v[122:125], v[142:145], v[188:191], v[122:125]
	v_mfma_f32_16x16x32_bf16 v[110:113], v[134:137], v[196:199], v[110:113]
	v_mfma_f32_16x16x32_bf16 v[106:109], v[142:145], v[196:199], v[106:109]
	v_mfma_f32_16x16x32_bf16 v[98:101], v[134:137], v[206:209], v[98:101]
	v_mfma_f32_16x16x32_bf16 v[90:93], v[142:145], v[206:209], v[90:93]
	v_mfma_f32_16x16x32_bf16 v[82:85], v[134:137], v[214:217], v[82:85]
	v_mfma_f32_16x16x32_bf16 v[74:77], v[142:145], v[214:217], v[74:77]
	s_setprio 0
	s_setprio 1
	v_mfma_f32_16x16x32_bf16 v[118:121], v[162:165], v[184:187], 0
	v_mfma_f32_16x16x32_bf16 v[114:117], v[176:179], v[184:187], 0
	v_mfma_f32_16x16x32_bf16 v[102:105], v[162:165], v[192:195], 0
	v_mfma_f32_16x16x32_bf16 v[94:97], v[176:179], v[192:195], 0
	v_mfma_f32_16x16x32_bf16 v[86:89], v[162:165], v[200:203], 0
	v_mfma_f32_16x16x32_bf16 v[78:81], v[176:179], v[200:203], 0
	v_mfma_f32_16x16x32_bf16 v[70:73], v[162:165], v[210:213], 0
	v_mfma_f32_16x16x32_bf16 v[66:69], v[176:179], v[210:213], 0
	v_mfma_f32_16x16x32_bf16 v[118:121], v[172:175], v[188:191], v[118:121]
	v_mfma_f32_16x16x32_bf16 v[114:117], v[180:183], v[188:191], v[114:117]
	v_mfma_f32_16x16x32_bf16 v[102:105], v[172:175], v[196:199], v[102:105]
	v_mfma_f32_16x16x32_bf16 v[94:97], v[180:183], v[196:199], v[94:97]
	v_mfma_f32_16x16x32_bf16 v[86:89], v[172:175], v[206:209], v[86:89]
	v_mfma_f32_16x16x32_bf16 v[78:81], v[180:183], v[206:209], v[78:81]
	v_mfma_f32_16x16x32_bf16 v[70:73], v[172:175], v[214:217], v[70:73]
	v_mfma_f32_16x16x32_bf16 v[66:69], v[180:183], v[214:217], v[66:69]
	s_setprio 0
	s_barrier
	s_add_i32 s94, s31, s2
	v_lshl_add_u64 v[218:219], s[62:63], 0, v[148:149]
	s_mov_b32 m0, s94
	ds_read_b128 v[184:187], v170 offset:16384
	ds_read_b128 v[188:191], v170 offset:17408
	ds_read_b128 v[192:195], v170 offset:18432
	ds_read_b128 v[196:199], v170 offset:19456
	ds_read_b128 v[200:203], v170 offset:20480
	ds_read_b128 v[206:209], v170 offset:21504
	ds_read_b128 v[210:213], v170 offset:22528
	ds_read_b128 v[214:217], v170 offset:23552
	global_load_lds_dwordx4 v[218:219], off
	s_add_i32 m0, s94, 0x2000
	s_add_u32 s94, s62, 0x100000
	v_lshl_add_u64 v[220:221], s[62:63], 0, v[152:153]
	s_addc_u32 s95, s63, 0
	s_add_i32 s96, s82, s2
	global_load_lds_dwordx4 v[220:221], off
	v_lshl_add_u64 v[222:223], s[94:95], 0, v[148:149]
	s_mov_b32 m0, s96
	v_lshl_add_u64 v[224:225], s[64:65], 0, v[150:151]
	global_load_lds_dwordx4 v[222:223], off
	v_lshl_add_u64 v[222:223], s[94:95], 0, v[152:153]
	s_add_i32 m0, s96, 0x2000
	s_nop 0
	global_load_lds_dwordx4 v[222:223], off
	v_lshl_add_u64 v[222:223], s[64:65], 0, v[146:147]
	s_mov_b32 m0, s12
	s_nop 0
	global_load_lds_dwordx4 v[222:223], off
	s_mov_b32 m0, s13
	s_nop 0
	global_load_lds_dwordx4 v[224:225], off
	s_waitcnt vmcnt(8)
	s_waitcnt lgkmcnt(0)
	s_barrier
	s_setprio 1
	s_waitcnt lgkmcnt(0)
	v_mfma_f32_16x16x32_bf16 v[62:65], v[130:133], v[184:187], 0
	v_mfma_f32_16x16x32_bf16 v[58:61], v[138:141], v[184:187], 0
	v_mfma_f32_16x16x32_bf16 v[50:53], v[130:133], v[192:195], 0
	v_mfma_f32_16x16x32_bf16 v[42:45], v[138:141], v[192:195], 0
	v_mfma_f32_16x16x32_bf16 v[34:37], v[130:133], v[200:203], 0
	v_mfma_f32_16x16x32_bf16 v[26:29], v[138:141], v[200:203], 0
	v_mfma_f32_16x16x32_bf16 v[18:21], v[130:133], v[210:213], 0
	v_mfma_f32_16x16x32_bf16 v[10:13], v[138:141], v[210:213], 0
	v_mfma_f32_16x16x32_bf16 v[62:65], v[134:137], v[188:191], v[62:65]
	v_mfma_f32_16x16x32_bf16 v[58:61], v[142:145], v[188:191], v[58:61]
	v_mfma_f32_16x16x32_bf16 v[50:53], v[134:137], v[196:199], v[50:53]
	v_mfma_f32_16x16x32_bf16 v[42:45], v[142:145], v[196:199], v[42:45]
	v_mfma_f32_16x16x32_bf16 v[34:37], v[134:137], v[206:209], v[34:37]
	v_mfma_f32_16x16x32_bf16 v[26:29], v[142:145], v[206:209], v[26:29]
	v_mfma_f32_16x16x32_bf16 v[18:21], v[134:137], v[214:217], v[18:21]
	v_mfma_f32_16x16x32_bf16 v[10:13], v[142:145], v[214:217], v[10:13]
	s_setprio 0
	s_setprio 1
	v_mfma_f32_16x16x32_bf16 v[54:57], v[162:165], v[184:187], 0
	v_mfma_f32_16x16x32_bf16 v[46:49], v[176:179], v[184:187], 0
	v_mfma_f32_16x16x32_bf16 v[38:41], v[162:165], v[192:195], 0
	v_mfma_f32_16x16x32_bf16 v[30:33], v[176:179], v[192:195], 0
	v_mfma_f32_16x16x32_bf16 v[22:25], v[162:165], v[200:203], 0
	v_mfma_f32_16x16x32_bf16 v[14:17], v[176:179], v[200:203], 0
	v_mfma_f32_16x16x32_bf16 v[6:9], v[162:165], v[210:213], 0
	v_mfma_f32_16x16x32_bf16 v[2:5], v[176:179], v[210:213], 0
	v_mfma_f32_16x16x32_bf16 v[54:57], v[172:175], v[188:191], v[54:57]
	v_mfma_f32_16x16x32_bf16 v[46:49], v[180:183], v[188:191], v[46:49]
	v_mfma_f32_16x16x32_bf16 v[38:41], v[172:175], v[196:199], v[38:41]
	v_mfma_f32_16x16x32_bf16 v[30:33], v[180:183], v[196:199], v[30:33]
	v_mfma_f32_16x16x32_bf16 v[22:25], v[172:175], v[206:209], v[22:25]
	v_mfma_f32_16x16x32_bf16 v[14:17], v[180:183], v[206:209], v[14:17]
	v_mfma_f32_16x16x32_bf16 v[6:9], v[172:175], v[214:217], v[6:9]
	v_mfma_f32_16x16x32_bf16 v[2:5], v[180:183], v[214:217], v[2:5]
	s_setprio 0
	s_barrier
	s_add_i32 s94, 0, 0x18000
	s_add_i32 s95, 0, 0x1c000
	v_add_u32_e32 v142, s94, v167
	v_add_u32_e32 v154, s95, v167
	ds_read_b128 v[130:133], v142
	ds_read_b128 v[134:137], v142 offset:1024
	ds_read_b128 v[138:141], v142 offset:2048
	ds_read_b128 v[142:145], v142 offset:3072
	ds_read_b128 v[162:165], v154
	ds_read_b128 v[172:175], v154 offset:1024
	ds_read_b128 v[176:179], v154 offset:2048
	ds_read_b128 v[180:183], v154 offset:3072
	s_add_u32 s64, s64, 0x100000
	s_addc_u32 s65, s65, 0
	s_mov_b32 m0, s18
	v_lshl_add_u64 v[226:227], s[64:65], 0, v[146:147]
	ds_read_b128 v[184:187], v170 offset:32768
	ds_read_b128 v[188:191], v170 offset:33792
	ds_read_b128 v[192:195], v170 offset:34816
	ds_read_b128 v[196:199], v170 offset:35840
	ds_read_b128 v[200:203], v170 offset:36864
	ds_read_b128 v[206:209], v170 offset:37888
	ds_read_b128 v[210:213], v170 offset:38912
	ds_read_b128 v[214:217], v170 offset:39936
	global_load_lds_dwordx4 v[226:227], off
	v_lshl_add_u64 v[226:227], s[64:65], 0, v[150:151]
	s_mov_b32 m0, s19
	s_nop 0
	global_load_lds_dwordx4 v[226:227], off
	s_waitcnt vmcnt(8)
	s_waitcnt lgkmcnt(0)
	s_barrier
	s_setprio 1
	s_waitcnt lgkmcnt(0)
	v_mfma_f32_16x16x32_bf16 v[126:129], v[130:133], v[184:187], v[126:129]
	v_mfma_f32_16x16x32_bf16 v[122:125], v[138:141], v[184:187], v[122:125]
	v_mfma_f32_16x16x32_bf16 v[110:113], v[130:133], v[192:195], v[110:113]
	v_mfma_f32_16x16x32_bf16 v[106:109], v[138:141], v[192:195], v[106:109]
	v_mfma_f32_16x16x32_bf16 v[98:101], v[130:133], v[200:203], v[98:101]
	v_mfma_f32_16x16x32_bf16 v[90:93], v[138:141], v[200:203], v[90:93]
	v_mfma_f32_16x16x32_bf16 v[82:85], v[130:133], v[210:213], v[82:85]
	v_mfma_f32_16x16x32_bf16 v[74:77], v[138:141], v[210:213], v[74:77]
	v_mfma_f32_16x16x32_bf16 v[126:129], v[134:137], v[188:191], v[126:129]
	v_mfma_f32_16x16x32_bf16 v[122:125], v[142:145], v[188:191], v[122:125]
	v_mfma_f32_16x16x32_bf16 v[110:113], v[134:137], v[196:199], v[110:113]
	v_mfma_f32_16x16x32_bf16 v[106:109], v[142:145], v[196:199], v[106:109]
	v_mfma_f32_16x16x32_bf16 v[98:101], v[134:137], v[206:209], v[98:101]
	v_mfma_f32_16x16x32_bf16 v[90:93], v[142:145], v[206:209], v[90:93]
	v_mfma_f32_16x16x32_bf16 v[82:85], v[134:137], v[214:217], v[82:85]
	v_mfma_f32_16x16x32_bf16 v[74:77], v[142:145], v[214:217], v[74:77]
	s_setprio 0
	s_setprio 1
	v_mfma_f32_16x16x32_bf16 v[118:121], v[162:165], v[184:187], v[118:121]
	v_mfma_f32_16x16x32_bf16 v[114:117], v[176:179], v[184:187], v[114:117]
	v_mfma_f32_16x16x32_bf16 v[102:105], v[162:165], v[192:195], v[102:105]
	v_mfma_f32_16x16x32_bf16 v[94:97], v[176:179], v[192:195], v[94:97]
	v_mfma_f32_16x16x32_bf16 v[86:89], v[162:165], v[200:203], v[86:89]
	v_mfma_f32_16x16x32_bf16 v[78:81], v[176:179], v[200:203], v[78:81]
	v_mfma_f32_16x16x32_bf16 v[70:73], v[162:165], v[210:213], v[70:73]
	v_mfma_f32_16x16x32_bf16 v[66:69], v[176:179], v[210:213], v[66:69]
	v_mfma_f32_16x16x32_bf16 v[118:121], v[172:175], v[188:191], v[118:121]
	v_mfma_f32_16x16x32_bf16 v[114:117], v[180:183], v[188:191], v[114:117]
	v_mfma_f32_16x16x32_bf16 v[102:105], v[172:175], v[196:199], v[102:105]
	v_mfma_f32_16x16x32_bf16 v[94:97], v[180:183], v[196:199], v[94:97]
	v_mfma_f32_16x16x32_bf16 v[86:89], v[172:175], v[206:209], v[86:89]
	v_mfma_f32_16x16x32_bf16 v[78:81], v[180:183], v[206:209], v[78:81]
	v_mfma_f32_16x16x32_bf16 v[70:73], v[172:175], v[214:217], v[70:73]
	v_mfma_f32_16x16x32_bf16 v[66:69], v[180:183], v[214:217], v[66:69]
	s_setprio 0
	s_barrier
	s_add_i32 s64, s94, s2
	v_lshl_add_u64 v[218:219], v[218:219], 0, s[16:17]
	s_mov_b32 m0, s64
	ds_read_b128 v[184:187], v170 offset:49152
	ds_read_b128 v[188:191], v170 offset:50176
	ds_read_b128 v[192:195], v170 offset:51200
	ds_read_b128 v[196:199], v170 offset:52224
	ds_read_b128 v[200:203], v170 offset:53248
	ds_read_b128 v[206:209], v170 offset:54272
	ds_read_b128 v[210:213], v170 offset:55296
	ds_read_b128 v[214:217], v170 offset:56320
	global_load_lds_dwordx4 v[218:219], off
	s_add_i32 m0, s64, 0x2000
	s_add_u32 s62, s62, 0x100080
	v_lshl_add_u64 v[218:219], v[220:221], 0, s[16:17]
	s_addc_u32 s63, s63, 0
	s_add_i32 s64, s95, s2
	global_load_lds_dwordx4 v[218:219], off
	v_lshl_add_u64 v[218:219], s[62:63], 0, v[148:149]
	s_mov_b32 m0, s64
	s_nop 0
	global_load_lds_dwordx4 v[218:219], off
	v_lshl_add_u64 v[218:219], s[62:63], 0, v[152:153]
	s_add_i32 m0, s64, 0x2000
	s_nop 0
	global_load_lds_dwordx4 v[218:219], off
	v_lshl_add_u64 v[218:219], v[222:223], 0, s[16:17]
	s_mov_b32 m0, s74
	s_nop 0
	global_load_lds_dwordx4 v[218:219], off
	v_lshl_add_u64 v[218:219], v[224:225], 0, s[16:17]
	s_mov_b32 m0, s75
	s_nop 0
	global_load_lds_dwordx4 v[218:219], off
	s_waitcnt vmcnt(8)
	s_waitcnt lgkmcnt(0)
	s_barrier
	s_setprio 1
	s_waitcnt lgkmcnt(0)
	v_mfma_f32_16x16x32_bf16 v[62:65], v[130:133], v[184:187], v[62:65]
	v_mfma_f32_16x16x32_bf16 v[58:61], v[138:141], v[184:187], v[58:61]
	v_mfma_f32_16x16x32_bf16 v[50:53], v[130:133], v[192:195], v[50:53]
	v_mfma_f32_16x16x32_bf16 v[42:45], v[138:141], v[192:195], v[42:45]
	v_mfma_f32_16x16x32_bf16 v[34:37], v[130:133], v[200:203], v[34:37]
	v_mfma_f32_16x16x32_bf16 v[26:29], v[138:141], v[200:203], v[26:29]
	v_mfma_f32_16x16x32_bf16 v[18:21], v[130:133], v[210:213], v[18:21]
	v_mfma_f32_16x16x32_bf16 v[10:13], v[138:141], v[210:213], v[10:13]
	v_mfma_f32_16x16x32_bf16 v[62:65], v[134:137], v[188:191], v[62:65]
	v_mfma_f32_16x16x32_bf16 v[58:61], v[142:145], v[188:191], v[58:61]
	v_mfma_f32_16x16x32_bf16 v[50:53], v[134:137], v[196:199], v[50:53]
	v_mfma_f32_16x16x32_bf16 v[42:45], v[142:145], v[196:199], v[42:45]
	v_mfma_f32_16x16x32_bf16 v[34:37], v[134:137], v[206:209], v[34:37]
	v_mfma_f32_16x16x32_bf16 v[26:29], v[142:145], v[206:209], v[26:29]
	v_mfma_f32_16x16x32_bf16 v[18:21], v[134:137], v[214:217], v[18:21]
	v_mfma_f32_16x16x32_bf16 v[10:13], v[142:145], v[214:217], v[10:13]
	s_setprio 0
	s_setprio 1
	v_mfma_f32_16x16x32_bf16 v[54:57], v[162:165], v[184:187], v[54:57]
	v_mfma_f32_16x16x32_bf16 v[46:49], v[176:179], v[184:187], v[46:49]
	v_mfma_f32_16x16x32_bf16 v[38:41], v[162:165], v[192:195], v[38:41]
	v_mfma_f32_16x16x32_bf16 v[30:33], v[176:179], v[192:195], v[30:33]
	v_mfma_f32_16x16x32_bf16 v[22:25], v[162:165], v[200:203], v[22:25]
	v_mfma_f32_16x16x32_bf16 v[14:17], v[176:179], v[200:203], v[14:17]
	v_mfma_f32_16x16x32_bf16 v[6:9], v[162:165], v[210:213], v[6:9]
	v_mfma_f32_16x16x32_bf16 v[2:5], v[176:179], v[210:213], v[2:5]
	v_mfma_f32_16x16x32_bf16 v[54:57], v[172:175], v[188:191], v[54:57]
	v_mfma_f32_16x16x32_bf16 v[46:49], v[180:183], v[188:191], v[46:49]
	v_mfma_f32_16x16x32_bf16 v[38:41], v[172:175], v[196:199], v[38:41]
	v_mfma_f32_16x16x32_bf16 v[30:33], v[180:183], v[196:199], v[30:33]
	v_mfma_f32_16x16x32_bf16 v[22:25], v[172:175], v[206:209], v[22:25]
	v_mfma_f32_16x16x32_bf16 v[14:17], v[180:183], v[206:209], v[14:17]
	v_mfma_f32_16x16x32_bf16 v[6:9], v[172:175], v[214:217], v[6:9]
	v_mfma_f32_16x16x32_bf16 v[2:5], v[180:183], v[214:217], v[2:5]
	s_setprio 0
	s_barrier
	s_add_u32 s50, s50, 0x100
	s_addc_u32 s51, s51, 0
	s_add_u32 s91, s91, 0x100
	s_addc_u32 s92, s92, 0
	s_cmp_ge_i32 s93, s7
	s_mov_b32 s62, s93
